# gate epilogue xr loads hoisted; redundant accumulator zeroing removed; barrier-init load chain batched
# speedup vs baseline: 1.0177x; 1.0132x over previous
; template <class Epi>
; __device__ __forceinline__ void gemm_phase(LAS unsigned char* lds, const Gemm g, const StaticOrder& S, const Epi& E, const int tid) {
;     ...
;     f32x4 acc[2][2][4][2];
; #pragma unroll
;     for (int a = 0; a < 2; ++a)
; #pragma unroll
;         for (int b = 0; b < 2; ++b)
; #pragma unroll
;             for (int m = 0; m < 4; ++m)
; #pragma unroll
;                 for (int n = 0; n < 2; ++n) acc[a][b][m][n] = (f32x4){0.f, 0.f, 0.f, 0.f};
.LBB0_183:
	v_mov_b32_e32 v137, 0
	s_andn2_b64 vcc, exec, s[96:97]
	s_cbranch_vccnz .LBB0_187
	s_add_u32 s0, s36, 0x100
	s_addc_u32 s1, s37, 0
	s_add_u32 s6, s38, 0x80
	v_mov_b32_e32 v2, 0
	s_addc_u32 s7, s39, 0
	s_mov_b32 s36, 0
	v_mov_b32_e32 v3, v2
	v_mov_b32_e32 v4, v2
	v_mov_b32_e32 v5, v2
	v_mov_b32_e32 v66, v2
	v_mov_b32_e32 v67, v2
	v_mov_b32_e32 v68, v2
	v_mov_b32_e32 v69, v2
	v_mov_b32_e32 v10, v2
	v_mov_b32_e32 v11, v2
	v_mov_b32_e32 v12, v2
	v_mov_b32_e32 v13, v2
	v_mov_b32_e32 v74, v2
	v_mov_b32_e32 v75, v2
	v_mov_b32_e32 v76, v2
	v_mov_b32_e32 v77, v2
	v_mov_b32_e32 v18, v2
	v_mov_b32_e32 v19, v2
	v_mov_b32_e32 v20, v2
	v_mov_b32_e32 v21, v2
	v_mov_b32_e32 v90, v2
	v_mov_b32_e32 v91, v2
	v_mov_b32_e32 v92, v2
	v_mov_b32_e32 v93, v2
	v_mov_b32_e32 v26, v2
	v_mov_b32_e32 v27, v2
	v_mov_b32_e32 v28, v2
	v_mov_b32_e32 v29, v2
	v_mov_b32_e32 v98, v2
	v_mov_b32_e32 v99, v2
	v_mov_b32_e32 v100, v2
	v_mov_b32_e32 v101, v2
	v_mov_b32_e32 v6, v2
	v_mov_b32_e32 v7, v2
	v_mov_b32_e32 v8, v2
	v_mov_b32_e32 v9, v2
	v_mov_b32_e32 v70, v2
	v_mov_b32_e32 v71, v2
	v_mov_b32_e32 v72, v2
	v_mov_b32_e32 v73, v2
	v_mov_b32_e32 v14, v2
	v_mov_b32_e32 v15, v2
	v_mov_b32_e32 v16, v2
	v_mov_b32_e32 v17, v2
	v_mov_b32_e32 v78, v2
	v_mov_b32_e32 v79, v2
	v_mov_b32_e32 v80, v2
	v_mov_b32_e32 v81, v2
	v_mov_b32_e32 v22, v2
	v_mov_b32_e32 v23, v2
	v_mov_b32_e32 v24, v2
	v_mov_b32_e32 v25, v2
	v_mov_b32_e32 v94, v2
	v_mov_b32_e32 v95, v2
	v_mov_b32_e32 v96, v2
	v_mov_b32_e32 v97, v2
	v_mov_b32_e32 v30, v2
	v_mov_b32_e32 v31, v2
	v_mov_b32_e32 v32, v2
	v_mov_b32_e32 v33, v2
	v_mov_b32_e32 v102, v2
	v_mov_b32_e32 v103, v2
	v_mov_b32_e32 v104, v2
	v_mov_b32_e32 v105, v2
	v_mov_b32_e32 v34, v2
	v_mov_b32_e32 v35, v2
	v_mov_b32_e32 v36, v2
	v_mov_b32_e32 v37, v2
	v_mov_b32_e32 v106, v2
	v_mov_b32_e32 v107, v2
	v_mov_b32_e32 v108, v2
	v_mov_b32_e32 v109, v2
	v_mov_b32_e32 v42, v2
	v_mov_b32_e32 v43, v2
	v_mov_b32_e32 v44, v2
	v_mov_b32_e32 v45, v2
	v_mov_b32_e32 v114, v2
	v_mov_b32_e32 v115, v2
	v_mov_b32_e32 v116, v2
	v_mov_b32_e32 v117, v2
	v_mov_b32_e32 v50, v2
	v_mov_b32_e32 v51, v2
	v_mov_b32_e32 v52, v2
	v_mov_b32_e32 v53, v2
	v_mov_b32_e32 v122, v2
	v_mov_b32_e32 v123, v2
	v_mov_b32_e32 v124, v2
	v_mov_b32_e32 v125, v2
	v_mov_b32_e32 v58, v2
	v_mov_b32_e32 v59, v2
	v_mov_b32_e32 v60, v2
	v_mov_b32_e32 v61, v2
	v_mov_b32_e32 v130, v2
	v_mov_b32_e32 v131, v2
	v_mov_b32_e32 v132, v2
	v_mov_b32_e32 v133, v2
	v_mov_b32_e32 v38, v2
	v_mov_b32_e32 v39, v2
	v_mov_b32_e32 v40, v2
	v_mov_b32_e32 v41, v2
	v_mov_b32_e32 v110, v2
	v_mov_b32_e32 v111, v2
	v_mov_b32_e32 v112, v2
	v_mov_b32_e32 v113, v2
	v_mov_b32_e32 v46, v2
	v_mov_b32_e32 v47, v2
	v_mov_b32_e32 v48, v2
	v_mov_b32_e32 v49, v2
	v_mov_b32_e32 v118, v2
	v_mov_b32_e32 v119, v2
	v_mov_b32_e32 v120, v2
	v_mov_b32_e32 v121, v2
	v_mov_b32_e32 v54, v2
	v_mov_b32_e32 v55, v2
	v_mov_b32_e32 v56, v2
	v_mov_b32_e32 v57, v2
	v_mov_b32_e32 v126, v2
	v_mov_b32_e32 v127, v2
	v_mov_b32_e32 v128, v2
	v_mov_b32_e32 v129, v2
	v_mov_b32_e32 v62, v2
	v_mov_b32_e32 v63, v2
	v_mov_b32_e32 v64, v2
	v_mov_b32_e32 v65, v2
	v_mov_b32_e32 v134, v2
	v_mov_b32_e32 v135, v2
	v_mov_b32_e32 v136, v2
	v_mov_b32_e32 v137, v2

;     __device__ __forceinline__ void operator()(const f32x4 (&acc)[2][2][4][2], const Unit& u, int wr, int wc, int fr, int fq) const {
;     ...
;         const int row0 = u.pm * BM + wr * 64 + fr, c0 = (u.pn >> 1) * 256 + (u.pn & 1) * 128 + wc * 32 + 8 * fq;
; #pragma unroll
;         for (int hf = 0; hf < 2; ++hf) {
;             const f32x4 lv = *(const f32x4*)(lam + c0 + 4 * hf), bav = *(const f32x4*)(b_a + c0 + 4 * hf), biv = *(const f32x4*)(b_i + c0 + 4 * hf);
;             f32x4 sp;
; #pragma unroll
;             for (int j = 0; j < 4; ++j) sp[j] = 8.0f * softplus_neg(lv[j]);
; #pragma unroll
;             for (int ai = 0; ai < 2; ++ai)
; #pragma unroll
;                 for (int m = 0; m < 4; ++m) {
;                     const int row = row0 + ai * HALF + m * 16; const size_t off = (size_t)row * D + c0 + 4 * hf;
;                     const u32x2 xw = *(const u32x2*)(xrc + off); const float xr[4] = {bf_lo(xw.x), bf_hi(xw.x), bf_lo(xw.y), bf_hi(xw.y)};
;                     u32x4 w;
; #pragma unroll
;                     for (int j2 = 0; j2 < 2; ++j2) { const int j = 2 * j2;
;                         const f32x2v rp = (f32x2v){acc[ai][0][m][hf][j], acc[ai][0][m][hf][j + 1]} + (f32x2v){bav[j], bav[j + 1]}, ip = (f32x2v){acc[ai][1][m][hf][j], acc[ai][1][m][hf][j + 1]} + (f32x2v){biv[j], biv[j + 1]};
;                         const f32x2v er = rp * (-1.4426950408889634f), ei = ip * (-1.4426950408889634f);
;                         f32x2v tr, ti; tr.x = __builtin_amdgcn_exp2f(er.x); tr.y = __builtin_amdgcn_exp2f(er.y); ti.x = __builtin_amdgcn_exp2f(ei.x); ti.y = __builtin_amdgcn_exp2f(ei.y);
;                         const f32x2v dr = tr + 1.0f, di = ti + 1.0f; f32x2v r, ig; r.x = __builtin_amdgcn_rcpf(dr.x); r.y = __builtin_amdgcn_rcpf(dr.y); ig.x = __builtin_amdgcn_rcpf(di.x); ig.y = __builtin_amdgcn_rcpf(di.y);
;                         const f32x2v la = r * (f32x2v){-sp[j], -sp[j + 1]}, e2 = la * 2.8853900817779268f;
;                         f32x2v a2; a2.x = __builtin_amdgcn_exp2f(e2.x); a2.y = __builtin_amdgcn_exp2f(e2.y);
;                         const f32x2v om = __builtin_elementwise_max(1.0f - a2, (f32x2v){0.f, 0.f}); f32x2v mult; mult.x = __builtin_amdgcn_sqrtf(om.x); mult.y = __builtin_amdgcn_sqrtf(om.y);
;                         const f32x2v bt = (mult * ig) * (f32x2v){xr[j], xr[j + 1]};
.LBB0_203:
	s_andn2_saveexec_b64 s[0:1], s[36:37]
	v_fmamk_f32 v139, v138, 0xbe800000, v249
	v_fma_f32 v139, -v138, v139, 0.5
	v_fma_f32 v139, -v138, v139, 1.0
	v_mul_f32_e32 v161, v138, v139
	s_or_b64 exec, exec, s[0:1]
	s_lshl_b32 s39, s58, 8
	v_and_b32_e32 v171, 15, v170
	s_add_i32 s0, s39, s49
	v_or_b32_e32 v140, s0, v171
	v_ashrrev_i32_e32 v141, 31, v140
	v_lshlrev_b64 v[138:139], 10, v[140:141]
	v_lshl_add_u64 v[164:165], v[138:139], 0, v[152:153]
	v_lshlrev_b32_e32 v238, 1, v164
	v_add_u32_e32 v239, 0x0, v238
	global_load_dwordx2 v[222:223], v239, s[8:9]
	v_add_u32_e32 v239, 0x8000, v238
	global_load_dwordx2 v[224:225], v239, s[8:9]
	v_add_u32_e32 v239, 0x10000, v238
	global_load_dwordx2 v[226:227], v239, s[8:9]
	v_add_u32_e32 v239, 0x18000, v238
	global_load_dwordx2 v[228:229], v239, s[8:9]
	v_add_u32_e32 v239, 0x40000, v238
	global_load_dwordx2 v[230:231], v239, s[8:9]
	v_add_u32_e32 v239, 0x48000, v238
	global_load_dwordx2 v[232:233], v239, s[8:9]
	v_add_u32_e32 v239, 0x50000, v238
	global_load_dwordx2 v[234:235], v239, s[8:9]
	v_add_u32_e32 v239, 0x58000, v238
	global_load_dwordx2 v[236:237], v239, s[8:9]
	v_pk_add_f32 v[134:135], v[134:135], v[86:87]
	s_mov_b32 s0, 0xc1000000
	v_pk_mul_f32 v[134:135], v[134:135], s[88:89] op_sel_hi:[1,0]
	v_pk_add_f32 v[130:131], v[130:131], v[82:83]
	v_exp_f32_e32 v134, v134
	v_exp_f32_e32 v135, v135
	v_pk_mul_f32 v[130:131], v[130:131], s[88:89] op_sel_hi:[1,0]
	v_pk_add_f32 v[136:137], v[136:137], v[88:89]
	v_exp_f32_e32 v130, v130
	v_pk_add_f32 v[134:135], v[134:135], 1.0 op_sel_hi:[1,0]
	v_exp_f32_e32 v131, v131
	v_rcp_f32_e32 v174, v134
	v_rcp_f32_e32 v175, v135
	v_pk_mul_f32 v[134:135], v[162:163], s[0:1] op_sel_hi:[1,0]
	v_pk_add_f32 v[130:131], v[130:131], 1.0 op_sel_hi:[1,0]
	v_pk_add_f32 v[132:133], v[132:133], v[84:85]
	v_pk_mul_f32 v[162:163], v[174:175], v[134:135]
	v_rcp_f32_e32 v130, v130
	v_pk_mul_f32 v[174:175], v[162:163], s[82:83] op_sel_hi:[1,0]
	v_rcp_f32_e32 v131, v131
	v_exp_f32_e32 v174, v174
	v_exp_f32_e32 v175, v175
	v_pk_mul_f32 v[132:133], v[132:133], s[88:89] op_sel_hi:[1,0]
	v_pk_add_f32 v[126:127], v[126:127], v[86:87]
	v_exp_f32_e32 v132, v132
	v_pk_add_f32 v[174:175], v[174:175], 1.0 op_sel_hi:[1,0] neg_lo:[1,0] neg_hi:[1,0]
	v_exp_f32_e32 v133, v133
	v_max_f32_e32 v141, 0, v175
	v_max_f32_e32 v174, 0, v174
	v_sqrt_f32_e32 v174, v174
	v_sqrt_f32_e32 v175, v141
	v_cvt_f16_f32_e32 v141, v162
	v_pk_add_f32 v[132:133], v[132:133], 1.0 op_sel_hi:[1,0]
	v_pk_mul_f32 v[126:127], v[126:127], s[88:89] op_sel_hi:[1,0]
	v_pk_mul_f32 v[130:131], v[130:131], v[174:175]
	v_exp_f32_e32 v126, v126
	v_exp_f32_e32 v127, v127
	v_pk_add_f32 v[122:123], v[122:123], v[82:83]
	v_pk_add_f32 v[128:129], v[128:129], v[88:89]
	v_pk_mul_f32 v[122:123], v[122:123], s[88:89] op_sel_hi:[1,0]
	v_pk_add_f32 v[126:127], v[126:127], 1.0 op_sel_hi:[1,0]
	v_exp_f32_e32 v122, v122
	v_rcp_f32_e32 v126, v126
	v_rcp_f32_e32 v127, v127
	v_exp_f32_e32 v123, v123
	v_pk_add_f32 v[124:125], v[124:125], v[84:85]
	v_pk_add_f32 v[118:119], v[118:119], v[86:87]
	v_pk_mul_f32 v[126:127], v[126:127], v[134:135]
	v_pk_add_f32 v[122:123], v[122:123], 1.0 op_sel_hi:[1,0]
	v_pk_mul_f32 v[124:125], v[124:125], s[88:89] op_sel_hi:[1,0]
	v_rcp_f32_e32 v122, v122
	v_rcp_f32_e32 v123, v123
	v_exp_f32_e32 v124, v124
	v_exp_f32_e32 v125, v125
	v_pk_mul_f32 v[118:119], v[118:119], s[88:89] op_sel_hi:[1,0]
	v_pk_add_f32 v[114:115], v[114:115], v[82:83]
	v_exp_f32_e32 v118, v118
	v_pk_add_f32 v[124:125], v[124:125], 1.0 op_sel_hi:[1,0]
	v_exp_f32_e32 v119, v119
	v_rcp_f32_e32 v124, v124
	v_rcp_f32_e32 v125, v125
	v_pk_mul_f32 v[114:115], v[114:115], s[88:89] op_sel_hi:[1,0]
	v_pk_add_f32 v[118:119], v[118:119], 1.0 op_sel_hi:[1,0]
	v_exp_f32_e32 v114, v114
	v_rcp_f32_e32 v118, v118
	v_rcp_f32_e32 v119, v119
	v_exp_f32_e32 v115, v115
	v_pk_add_f32 v[120:121], v[120:121], v[88:89]
	v_pk_add_f32 v[116:117], v[116:117], v[84:85]
	v_pk_mul_f32 v[118:119], v[118:119], v[134:135]
	v_pk_add_f32 v[114:115], v[114:115], 1.0 op_sel_hi:[1,0]
	v_pk_mul_f32 v[116:117], v[116:117], s[88:89] op_sel_hi:[1,0]
	v_rcp_f32_e32 v114, v114
	v_rcp_f32_e32 v115, v115
	v_exp_f32_e32 v116, v116
	v_exp_f32_e32 v117, v117
	v_pk_add_f32 v[110:111], v[110:111], v[86:87]
	v_pk_add_f32 v[106:107], v[106:107], v[82:83]
	v_pk_mul_f32 v[110:111], v[110:111], s[88:89] op_sel_hi:[1,0]
	s_waitcnt vmcnt(7) lgkmcnt(0)
; __device__ __forceinline__ float bf_lo(unsigned w) { return __uint_as_float(w << 16); }
; __device__ __forceinline__ float bf_hi(unsigned w) { return __uint_as_float(w & 0xffff0000u); }
; __device__ __forceinline__ unsigned pack_f16(float lo, float hi) { const _Float16 a = (_Float16)lo, b = (_Float16)hi; return (unsigned)__builtin_bit_cast(unsigned short, a) | ((unsigned)__builtin_bit_cast(unsigned short, b) << 16); }
;     __device__ __forceinline__ void operator()(const f32x4 (&acc)[2][2][4][2], const Unit& u, int wr, int wc, int fr, int fq) const {
;     ...
;                     const int row = row0 + ai * HALF + m * 16; const size_t off = (size_t)row * D + c0 + 4 * hf;
;                     const u32x2 xw = *(const u32x2*)(xrc + off); const float xr[4] = {bf_lo(xw.x), bf_hi(xw.x), bf_lo(xw.y), bf_hi(xw.y)};
;                     u32x4 w;
; #pragma unroll
;                     for (int j2 = 0; j2 < 2; ++j2) { const int j = 2 * j2;
;                         const f32x2v rp = (f32x2v){acc[ai][0][m][hf][j], acc[ai][0][m][hf][j + 1]} + (f32x2v){bav[j], bav[j + 1]}, ip = (f32x2v){acc[ai][1][m][hf][j], acc[ai][1][m][hf][j + 1]} + (f32x2v){biv[j], biv[j + 1]};
;                         const f32x2v er = rp * (-1.4426950408889634f), ei = ip * (-1.4426950408889634f);
;                         f32x2v tr, ti; tr.x = __builtin_amdgcn_exp2f(er.x); tr.y = __builtin_amdgcn_exp2f(er.y); ti.x = __builtin_amdgcn_exp2f(ei.x); ti.y = __builtin_amdgcn_exp2f(ei.y);
;                         const f32x2v dr = tr + 1.0f, di = ti + 1.0f; f32x2v r, ig; r.x = __builtin_amdgcn_rcpf(dr.x); r.y = __builtin_amdgcn_rcpf(dr.y); ig.x = __builtin_amdgcn_rcpf(di.x); ig.y = __builtin_amdgcn_rcpf(di.y);
;                         const f32x2v la = r * (f32x2v){-sp[j], -sp[j + 1]}, e2 = la * 2.8853900817779268f;
;                         f32x2v a2; a2.x = __builtin_amdgcn_exp2f(e2.x); a2.y = __builtin_amdgcn_exp2f(e2.y);
;                         const f32x2v om = __builtin_elementwise_max(1.0f - a2, (f32x2v){0.f, 0.f}); f32x2v mult; mult.x = __builtin_amdgcn_sqrtf(om.x); mult.y = __builtin_amdgcn_sqrtf(om.y);
;                         const f32x2v bt = (mult * ig) * (f32x2v){xr[j], xr[j + 1]};
;                         w[j] = pack_f16(la.x, bt.x); w[j + 1] = pack_f16(la.y, bt.y); }
;                     *(u32x4*)(AB + off) = w;
	v_lshlrev_b32_e32 v172, 16, v222
	v_and_b32_e32 v173, 0xffff0000, v222
	v_pk_mul_f32 v[130:131], v[130:131], v[172:173]
	v_lshlrev_b32_e32 v166, 16, v223
	v_cvt_f16_f32_sdwa v130, v130 dst_sel:WORD_1 dst_unused:UNUSED_PAD src0_sel:DWORD
	v_cvt_f16_f32_sdwa v131, v131 dst_sel:WORD_1 dst_unused:UNUSED_PAD src0_sel:DWORD
	v_and_b32_e32 v167, 0xffff0000, v223
	v_add_u32_e32 v239, 0x8, v238
	global_load_dwordx2 v[222:223], v239, s[8:9]
	v_pk_add_f32 v[116:117], v[116:117], 1.0 op_sel_hi:[1,0]
	v_or_b32_e32 v172, v130, v141
	v_cvt_f16_f32_e32 v130, v163
	v_rcp_f32_e32 v116, v116
	v_rcp_f32_e32 v117, v117
	v_exp_f32_e32 v110, v110
	v_or_b32_e32 v173, v131, v130
	v_pk_mul_f32 v[130:131], v[136:137], s[88:89] op_sel_hi:[1,0]
	v_rcp_f32_e32 v136, v132
	v_exp_f32_e32 v130, v130
	v_exp_f32_e32 v131, v131
	v_rcp_f32_e32 v137, v133
	v_pk_mul_f32 v[132:133], v[160:161], s[0:1] op_sel_hi:[1,0]
	v_exp_f32_e32 v111, v111
	v_pk_add_f32 v[130:131], v[130:131], 1.0 op_sel_hi:[1,0]
	v_pk_mul_f32 v[106:107], v[106:107], s[88:89] op_sel_hi:[1,0]
	v_rcp_f32_e32 v130, v130
	v_rcp_f32_e32 v131, v131
	v_pk_add_f32 v[110:111], v[110:111], 1.0 op_sel_hi:[1,0]
	v_exp_f32_e32 v106, v106
	v_rcp_f32_e32 v110, v110
	v_pk_mul_f32 v[130:131], v[130:131], v[132:133]
	v_rcp_f32_e32 v111, v111
	v_pk_mul_f32 v[160:161], v[130:131], s[82:83] op_sel_hi:[1,0]
	v_cvt_f16_f32_e32 v130, v130
	v_exp_f32_e32 v160, v160
	v_exp_f32_e32 v161, v161
	v_pk_mul_f32 v[110:111], v[110:111], v[134:135]
	v_exp_f32_e32 v107, v107
	v_pk_add_f32 v[112:113], v[112:113], v[88:89]
	v_pk_add_f32 v[160:161], v[160:161], 1.0 op_sel_hi:[1,0] neg_lo:[1,0] neg_hi:[1,0]
	v_pk_add_f32 v[108:109], v[108:109], v[84:85]
	v_max_f32_e32 v141, 0, v161
	v_max_f32_e32 v160, 0, v160
	v_sqrt_f32_e32 v160, v160
	v_sqrt_f32_e32 v161, v141
	v_pk_add_f32 v[106:107], v[106:107], 1.0 op_sel_hi:[1,0]
	v_pk_mul_f32 v[108:109], v[108:109], s[88:89] op_sel_hi:[1,0]
	v_rcp_f32_e32 v106, v106
	v_pk_mul_f32 v[136:137], v[136:137], v[160:161]
	v_rcp_f32_e32 v107, v107
	v_pk_mul_f32 v[136:137], v[136:137], v[166:167]
	v_exp_f32_e32 v108, v108
	v_cvt_f16_f32_sdwa v136, v136 dst_sel:WORD_1 dst_unused:UNUSED_PAD src0_sel:DWORD
	v_exp_f32_e32 v109, v109
	s_mov_b64 s[6:7], 0x20000
	v_pk_add_f32 v[102:103], v[102:103], v[86:87]
	v_or_b32_e32 v174, v136, v130
	v_cvt_f16_f32_e32 v130, v131
	v_cvt_f16_f32_sdwa v131, v137 dst_sel:WORD_1 dst_unused:UNUSED_PAD src0_sel:DWORD
	v_pk_add_f32 v[108:109], v[108:109], 1.0 op_sel_hi:[1,0]
	v_pk_mul_f32 v[102:103], v[102:103], s[88:89] op_sel_hi:[1,0]
	v_rcp_f32_e32 v108, v108
	v_or_b32_e32 v175, v131, v130
	v_lshl_add_u64 v[130:131], v[164:165], 2, s[20:21]
	global_store_dwordx4 v[130:131], v[172:175], off
	v_or_b32_e32 v130, 16, v140
	v_ashrrev_i32_e32 v131, 31, v130
	v_lshlrev_b64 v[130:131], 10, v[130:131]
	v_lshl_add_u64 v[136:137], v[130:131], 0, v[152:153]
	v_pk_mul_f32 v[164:165], v[126:127], s[82:83] op_sel_hi:[1,0]
	v_cvt_f16_f32_e32 v126, v126
	v_exp_f32_e32 v164, v164
	v_exp_f32_e32 v165, v165
	v_rcp_f32_e32 v109, v109
	v_exp_f32_e32 v102, v102
	v_exp_f32_e32 v103, v103
	v_pk_add_f32 v[164:165], v[164:165], 1.0 op_sel_hi:[1,0] neg_lo:[1,0] neg_hi:[1,0]
	v_pk_add_f32 v[98:99], v[98:99], v[82:83]
	v_max_f32_e32 v141, 0, v165
	v_max_f32_e32 v164, 0, v164
	v_sqrt_f32_e32 v164, v164
	v_sqrt_f32_e32 v165, v141
	v_pk_add_f32 v[102:103], v[102:103], 1.0 op_sel_hi:[1,0]
	v_pk_mul_f32 v[98:99], v[98:99], s[88:89] op_sel_hi:[1,0]
	v_rcp_f32_e32 v102, v102
	v_pk_mul_f32 v[122:123], v[122:123], v[164:165]
	v_rcp_f32_e32 v103, v103
	v_exp_f32_e32 v98, v98
	v_exp_f32_e32 v99, v99
	v_pk_add_f32 v[104:105], v[104:105], v[88:89]
	v_pk_mul_f32 v[102:103], v[102:103], v[134:135]
	v_pk_add_f32 v[100:101], v[100:101], v[84:85]
	v_pk_add_f32 v[98:99], v[98:99], 1.0 op_sel_hi:[1,0]
	v_pk_mul_f32 v[100:101], v[100:101], s[88:89] op_sel_hi:[1,0]
	v_rcp_f32_e32 v98, v98
	v_rcp_f32_e32 v99, v99
	v_exp_f32_e32 v100, v100
	v_exp_f32_e32 v101, v101
	v_pk_add_f32 v[94:95], v[94:95], v[86:87]
	v_pk_add_f32 v[90:91], v[90:91], v[82:83]
	v_pk_mul_f32 v[94:95], v[94:95], s[88:89] op_sel_hi:[1,0]
	v_pk_add_f32 v[100:101], v[100:101], 1.0 op_sel_hi:[1,0]
	v_exp_f32_e32 v94, v94
	v_rcp_f32_e32 v100, v100
	v_rcp_f32_e32 v101, v101
	v_exp_f32_e32 v95, v95
	v_pk_mul_f32 v[90:91], v[90:91], s[88:89] op_sel_hi:[1,0]
	v_pk_add_f32 v[96:97], v[96:97], v[88:89]
	v_exp_f32_e32 v90, v90
	v_pk_add_f32 v[94:95], v[94:95], 1.0 op_sel_hi:[1,0]
	v_exp_f32_e32 v91, v91
	v_rcp_f32_e32 v94, v94
	v_rcp_f32_e32 v95, v95
	v_pk_add_f32 v[92:93], v[92:93], v[84:85]
	v_pk_add_f32 v[90:91], v[90:91], 1.0 op_sel_hi:[1,0]
	v_pk_mul_f32 v[92:93], v[92:93], s[88:89] op_sel_hi:[1,0]
	v_pk_mul_f32 v[94:95], v[94:95], v[134:135]
	v_rcp_f32_e32 v90, v90
	v_rcp_f32_e32 v91, v91
	v_exp_f32_e32 v92, v92
	v_exp_f32_e32 v93, v93
	v_pk_add_f32 v[78:79], v[78:79], v[86:87]
	v_pk_add_f32 v[74:75], v[74:75], v[82:83]
	v_pk_mul_f32 v[78:79], v[78:79], s[88:89] op_sel_hi:[1,0]
	v_pk_add_f32 v[92:93], v[92:93], 1.0 op_sel_hi:[1,0]
	v_exp_f32_e32 v78, v78
	v_rcp_f32_e32 v92, v92
	v_rcp_f32_e32 v93, v93
	v_exp_f32_e32 v79, v79
	v_pk_mul_f32 v[74:75], v[74:75], s[88:89] op_sel_hi:[1,0]
	v_pk_add_f32 v[80:81], v[80:81], v[88:89]
	v_exp_f32_e32 v74, v74
	v_pk_add_f32 v[78:79], v[78:79], 1.0 op_sel_hi:[1,0]
	v_exp_f32_e32 v75, v75
	v_rcp_f32_e32 v78, v78
	v_rcp_f32_e32 v79, v79
	v_pk_add_f32 v[76:77], v[76:77], v[84:85]
	v_pk_add_f32 v[74:75], v[74:75], 1.0 op_sel_hi:[1,0]
	v_pk_mul_f32 v[76:77], v[76:77], s[88:89] op_sel_hi:[1,0]
	v_pk_mul_f32 v[78:79], v[78:79], v[134:135]
	v_rcp_f32_e32 v74, v74
	v_rcp_f32_e32 v75, v75
	v_exp_f32_e32 v76, v76
	v_exp_f32_e32 v77, v77
	v_pk_add_f32 v[70:71], v[70:71], v[86:87]
	v_pk_add_f32 v[66:67], v[66:67], v[82:83]
	v_pk_mul_f32 v[70:71], v[70:71], s[88:89] op_sel_hi:[1,0]
	v_pk_add_f32 v[76:77], v[76:77], 1.0 op_sel_hi:[1,0]
	s_waitcnt vmcnt(8) lgkmcnt(0)
; __device__ __forceinline__ float bf_lo(unsigned w) { return __uint_as_float(w << 16); }
; __device__ __forceinline__ float bf_hi(unsigned w) { return __uint_as_float(w & 0xffff0000u); }
; __device__ __forceinline__ unsigned pack_f16(float lo, float hi) { const _Float16 a = (_Float16)lo, b = (_Float16)hi; return (unsigned)__builtin_bit_cast(unsigned short, a) | ((unsigned)__builtin_bit_cast(unsigned short, b) << 16); }
;     __device__ __forceinline__ void operator()(const f32x4 (&acc)[2][2][4][2], const Unit& u, int wr, int wc, int fr, int fq) const {
;     ...
;                     const int row = row0 + ai * HALF + m * 16; const size_t off = (size_t)row * D + c0 + 4 * hf;
;                     const u32x2 xw = *(const u32x2*)(xrc + off); const float xr[4] = {bf_lo(xw.x), bf_hi(xw.x), bf_lo(xw.y), bf_hi(xw.y)};
;                     u32x4 w;
; #pragma unroll
;                     for (int j2 = 0; j2 < 2; ++j2) { const int j = 2 * j2;
;                         const f32x2v rp = (f32x2v){acc[ai][0][m][hf][j], acc[ai][0][m][hf][j + 1]} + (f32x2v){bav[j], bav[j + 1]}, ip = (f32x2v){acc[ai][1][m][hf][j], acc[ai][1][m][hf][j + 1]} + (f32x2v){biv[j], biv[j + 1]};
;                         const f32x2v er = rp * (-1.4426950408889634f), ei = ip * (-1.4426950408889634f);
;                         f32x2v tr, ti; tr.x = __builtin_amdgcn_exp2f(er.x); tr.y = __builtin_amdgcn_exp2f(er.y); ti.x = __builtin_amdgcn_exp2f(ei.x); ti.y = __builtin_amdgcn_exp2f(ei.y);
;                         const f32x2v dr = tr + 1.0f, di = ti + 1.0f; f32x2v r, ig; r.x = __builtin_amdgcn_rcpf(dr.x); r.y = __builtin_amdgcn_rcpf(dr.y); ig.x = __builtin_amdgcn_rcpf(di.x); ig.y = __builtin_amdgcn_rcpf(di.y);
;                         const f32x2v la = r * (f32x2v){-sp[j], -sp[j + 1]}, e2 = la * 2.8853900817779268f;
;                         f32x2v a2; a2.x = __builtin_amdgcn_exp2f(e2.x); a2.y = __builtin_amdgcn_exp2f(e2.y);
;                         const f32x2v om = __builtin_elementwise_max(1.0f - a2, (f32x2v){0.f, 0.f}); f32x2v mult; mult.x = __builtin_amdgcn_sqrtf(om.x); mult.y = __builtin_amdgcn_sqrtf(om.y);
;                         const f32x2v bt = (mult * ig) * (f32x2v){xr[j], xr[j + 1]};
;                         w[j] = pack_f16(la.x, bt.x); w[j + 1] = pack_f16(la.y, bt.y); }
;                     *(u32x4*)(AB + off) = w;
	v_lshlrev_b32_e32 v162, 16, v224
	v_and_b32_e32 v163, 0xffff0000, v224
	v_pk_mul_f32 v[122:123], v[122:123], v[162:163]
	v_lshlrev_b32_e32 v160, 16, v225
	v_cvt_f16_f32_sdwa v122, v122 dst_sel:WORD_1 dst_unused:UNUSED_PAD src0_sel:DWORD
	v_cvt_f16_f32_sdwa v123, v123 dst_sel:WORD_1 dst_unused:UNUSED_PAD src0_sel:DWORD
	v_and_b32_e32 v161, 0xffff0000, v225
	v_add_u32_e32 v239, 0x8008, v238
	global_load_dwordx2 v[224:225], v239, s[8:9]
	v_rcp_f32_e32 v76, v76
	v_or_b32_e32 v122, v122, v126
	v_cvt_f16_f32_e32 v126, v127
	v_rcp_f32_e32 v77, v77
	v_exp_f32_e32 v70, v70
	v_exp_f32_e32 v71, v71
	v_or_b32_e32 v123, v123, v126
	v_pk_mul_f32 v[126:127], v[128:129], s[88:89] op_sel_hi:[1,0]
	v_pk_mul_f32 v[66:67], v[66:67], s[88:89] op_sel_hi:[1,0]
	v_exp_f32_e32 v126, v126
	v_exp_f32_e32 v127, v127
	v_pk_add_f32 v[70:71], v[70:71], 1.0 op_sel_hi:[1,0]
	v_exp_f32_e32 v66, v66
	v_rcp_f32_e32 v70, v70
	v_pk_add_f32 v[126:127], v[126:127], 1.0 op_sel_hi:[1,0]
	v_rcp_f32_e32 v71, v71
	v_rcp_f32_e32 v126, v126
	v_rcp_f32_e32 v127, v127
	v_exp_f32_e32 v67, v67
	v_pk_mul_f32 v[70:71], v[70:71], v[134:135]
	v_pk_add_f32 v[72:73], v[72:73], v[88:89]
	v_pk_mul_f32 v[126:127], v[126:127], v[132:133]
	v_pk_mul_f32 v[82:83], v[70:71], s[82:83] op_sel_hi:[1,0]
	v_pk_mul_f32 v[128:129], v[126:127], s[82:83] op_sel_hi:[1,0]
	v_cvt_f16_f32_e32 v126, v126
	v_exp_f32_e32 v128, v128
	v_exp_f32_e32 v129, v129
	v_exp_f32_e32 v82, v82
	v_exp_f32_e32 v83, v83
	v_pk_add_f32 v[66:67], v[66:67], 1.0 op_sel_hi:[1,0]
	v_pk_add_f32 v[128:129], v[128:129], 1.0 op_sel_hi:[1,0] neg_lo:[1,0] neg_hi:[1,0]
	v_rcp_f32_e32 v66, v66
	v_max_f32_e32 v129, 0, v129
	v_max_f32_e32 v128, 0, v128
	v_sqrt_f32_e32 v128, v128
	v_sqrt_f32_e32 v129, v129
	v_pk_add_f32 v[82:83], v[82:83], 1.0 op_sel_hi:[1,0] neg_lo:[1,0] neg_hi:[1,0]
	v_rcp_f32_e32 v67, v67
	v_max_f32_e32 v83, 0, v83
	v_pk_mul_f32 v[124:125], v[124:125], v[128:129]
	v_max_f32_e32 v82, 0, v82
	v_pk_mul_f32 v[124:125], v[124:125], v[160:161]
	v_sqrt_f32_e32 v82, v82
	v_cvt_f16_f32_sdwa v124, v124 dst_sel:WORD_1 dst_unused:UNUSED_PAD src0_sel:DWORD
	v_cvt_f16_f32_sdwa v125, v125 dst_sel:WORD_1 dst_unused:UNUSED_PAD src0_sel:DWORD
	v_sqrt_f32_e32 v83, v83
	v_cvt_f16_f32_e32 v70, v70
	v_or_b32_e32 v124, v124, v126
	v_cvt_f16_f32_e32 v126, v127
	v_pk_mul_f32 v[66:67], v[66:67], v[82:83]
	v_pk_add_f32 v[68:69], v[68:69], v[84:85]
	v_or_b32_e32 v125, v125, v126
	v_lshl_add_u64 v[126:127], v[136:137], 2, s[20:21]
	global_store_dwordx4 v[126:127], v[122:125], off
	v_pk_mul_f32 v[136:137], v[118:119], s[82:83] op_sel_hi:[1,0]
	v_cvt_f16_f32_e32 v118, v118
	v_or_b32_e32 v122, 32, v140
	v_ashrrev_i32_e32 v123, 31, v122
	v_lshlrev_b64 v[122:123], 10, v[122:123]
	v_lshl_add_u64 v[124:125], v[122:123], 0, v[152:153]
	v_exp_f32_e32 v136, v136
	v_exp_f32_e32 v137, v137
	v_pk_mul_f32 v[68:69], v[68:69], s[88:89] op_sel_hi:[1,0]
	v_pk_add_f32 v[136:137], v[136:137], 1.0 op_sel_hi:[1,0] neg_lo:[1,0] neg_hi:[1,0]
	s_nop 0
	v_max_f32_e32 v137, 0, v137
	v_max_f32_e32 v136, 0, v136
	v_sqrt_f32_e32 v136, v136
	v_sqrt_f32_e32 v137, v137
	v_exp_f32_e32 v68, v68
	v_exp_f32_e32 v69, v69
	v_pk_mul_f32 v[114:115], v[114:115], v[136:137]
	v_pk_add_f32 v[68:69], v[68:69], 1.0 op_sel_hi:[1,0]
	s_nop 0
	v_rcp_f32_e32 v68, v68
	v_rcp_f32_e32 v69, v69
	s_waitcnt vmcnt(9) lgkmcnt(0)
	v_lshlrev_b32_e32 v128, 16, v226
	v_and_b32_e32 v129, 0xffff0000, v226
	v_pk_mul_f32 v[114:115], v[114:115], v[128:129]
	v_lshlrev_b32_e32 v126, 16, v227
	v_cvt_f16_f32_sdwa v114, v114 dst_sel:WORD_1 dst_unused:UNUSED_PAD src0_sel:DWORD
	v_cvt_f16_f32_sdwa v115, v115 dst_sel:WORD_1 dst_unused:UNUSED_PAD src0_sel:DWORD
	v_and_b32_e32 v127, 0xffff0000, v227
	v_add_u32_e32 v239, 0x10008, v238
	global_load_dwordx2 v[226:227], v239, s[8:9]
	v_or_b32_e32 v114, v114, v118
	v_cvt_f16_f32_e32 v118, v119
	v_or_b32_e32 v115, v115, v118
	v_pk_mul_f32 v[118:119], v[120:121], s[88:89] op_sel_hi:[1,0]
	s_nop 0
	v_exp_f32_e32 v118, v118
	v_exp_f32_e32 v119, v119
	s_nop 0
	v_pk_add_f32 v[118:119], v[118:119], 1.0 op_sel_hi:[1,0]
	s_nop 0
	v_rcp_f32_e32 v118, v118
	v_rcp_f32_e32 v119, v119
	s_nop 0
	v_pk_mul_f32 v[118:119], v[118:119], v[132:133]
	s_nop 0
	v_pk_mul_f32 v[120:121], v[118:119], s[82:83] op_sel_hi:[1,0]
	v_cvt_f16_f32_e32 v118, v118
	v_exp_f32_e32 v120, v120
	v_exp_f32_e32 v121, v121
	s_nop 0
	v_pk_add_f32 v[120:121], v[120:121], 1.0 op_sel_hi:[1,0] neg_lo:[1,0] neg_hi:[1,0]
	s_nop 0
	v_max_f32_e32 v121, 0, v121
	v_max_f32_e32 v120, 0, v120
	v_sqrt_f32_e32 v120, v120
	v_sqrt_f32_e32 v121, v121
	s_nop 0
	v_pk_mul_f32 v[116:117], v[116:117], v[120:121]
	s_nop 0
	v_pk_mul_f32 v[116:117], v[116:117], v[126:127]
	s_nop 0
	v_cvt_f16_f32_sdwa v116, v116 dst_sel:WORD_1 dst_unused:UNUSED_PAD src0_sel:DWORD
	v_cvt_f16_f32_sdwa v117, v117 dst_sel:WORD_1 dst_unused:UNUSED_PAD src0_sel:DWORD
	v_or_b32_e32 v116, v116, v118
	v_cvt_f16_f32_e32 v118, v119
	v_or_b32_e32 v117, v117, v118
	v_lshl_add_u64 v[118:119], v[124:125], 2, s[20:21]
	global_store_dwordx4 v[118:119], v[114:117], off
	v_pk_mul_f32 v[124:125], v[110:111], s[82:83] op_sel_hi:[1,0]
	v_cvt_f16_f32_e32 v110, v110
	v_or_b32_e32 v114, 48, v140
	v_ashrrev_i32_e32 v115, 31, v114
	v_lshlrev_b64 v[114:115], 10, v[114:115]
	v_lshl_add_u64 v[116:117], v[114:115], 0, v[152:153]
	v_exp_f32_e32 v124, v124
	v_exp_f32_e32 v125, v125
	s_waitcnt vmcnt(10) lgkmcnt(0)
; __device__ __forceinline__ float bf_lo(unsigned w) { return __uint_as_float(w << 16); }
; __device__ __forceinline__ float bf_hi(unsigned w) { return __uint_as_float(w & 0xffff0000u); }
; __device__ __forceinline__ unsigned pack_f16(float lo, float hi) { const _Float16 a = (_Float16)lo, b = (_Float16)hi; return (unsigned)__builtin_bit_cast(unsigned short, a) | ((unsigned)__builtin_bit_cast(unsigned short, b) << 16); }
;     __device__ __forceinline__ void operator()(const f32x4 (&acc)[2][2][4][2], const Unit& u, int wr, int wc, int fr, int fq) const {
;     ...
;                     const int row = row0 + ai * HALF + m * 16; const size_t off = (size_t)row * D + c0 + 4 * hf;
;                     const u32x2 xw = *(const u32x2*)(xrc + off); const float xr[4] = {bf_lo(xw.x), bf_hi(xw.x), bf_lo(xw.y), bf_hi(xw.y)};
;                     u32x4 w;
; #pragma unroll
;                     for (int j2 = 0; j2 < 2; ++j2) { const int j = 2 * j2;
;                         const f32x2v rp = (f32x2v){acc[ai][0][m][hf][j], acc[ai][0][m][hf][j + 1]} + (f32x2v){bav[j], bav[j + 1]}, ip = (f32x2v){acc[ai][1][m][hf][j], acc[ai][1][m][hf][j + 1]} + (f32x2v){biv[j], biv[j + 1]};
;                         const f32x2v er = rp * (-1.4426950408889634f), ei = ip * (-1.4426950408889634f);
;                         f32x2v tr, ti; tr.x = __builtin_amdgcn_exp2f(er.x); tr.y = __builtin_amdgcn_exp2f(er.y); ti.x = __builtin_amdgcn_exp2f(ei.x); ti.y = __builtin_amdgcn_exp2f(ei.y);
;                         const f32x2v dr = tr + 1.0f, di = ti + 1.0f; f32x2v r, ig; r.x = __builtin_amdgcn_rcpf(dr.x); r.y = __builtin_amdgcn_rcpf(dr.y); ig.x = __builtin_amdgcn_rcpf(di.x); ig.y = __builtin_amdgcn_rcpf(di.y);
;                         const f32x2v la = r * (f32x2v){-sp[j], -sp[j + 1]}, e2 = la * 2.8853900817779268f;
;                         f32x2v a2; a2.x = __builtin_amdgcn_exp2f(e2.x); a2.y = __builtin_amdgcn_exp2f(e2.y);
;                         const f32x2v om = __builtin_elementwise_max(1.0f - a2, (f32x2v){0.f, 0.f}); f32x2v mult; mult.x = __builtin_amdgcn_sqrtf(om.x); mult.y = __builtin_amdgcn_sqrtf(om.y);
;                         const f32x2v bt = (mult * ig) * (f32x2v){xr[j], xr[j + 1]};
;                         w[j] = pack_f16(la.x, bt.x); w[j + 1] = pack_f16(la.y, bt.y); }
;                     *(u32x4*)(AB + off) = w;
	v_lshlrev_b32_e32 v120, 16, v228
	v_pk_add_f32 v[124:125], v[124:125], 1.0 op_sel_hi:[1,0] neg_lo:[1,0] neg_hi:[1,0]
	v_and_b32_e32 v121, 0xffff0000, v228
	v_max_f32_e32 v125, 0, v125
	v_max_f32_e32 v124, 0, v124
	v_sqrt_f32_e32 v124, v124
	v_sqrt_f32_e32 v125, v125
	v_lshlrev_b32_e32 v118, 16, v229
	v_and_b32_e32 v119, 0xffff0000, v229
	v_add_u32_e32 v239, 0x18008, v238
	global_load_dwordx2 v[228:229], v239, s[8:9]
	v_pk_mul_f32 v[106:107], v[106:107], v[124:125]
	s_nop 0
	v_pk_mul_f32 v[106:107], v[106:107], v[120:121]
	s_nop 0
	v_cvt_f16_f32_sdwa v106, v106 dst_sel:WORD_1 dst_unused:UNUSED_PAD src0_sel:DWORD
	v_cvt_f16_f32_sdwa v107, v107 dst_sel:WORD_1 dst_unused:UNUSED_PAD src0_sel:DWORD
	v_or_b32_e32 v106, v106, v110
	v_cvt_f16_f32_e32 v110, v111
	v_or_b32_e32 v107, v107, v110
	v_pk_mul_f32 v[110:111], v[112:113], s[88:89] op_sel_hi:[1,0]
	s_nop 0
	v_exp_f32_e32 v110, v110
	v_exp_f32_e32 v111, v111
	s_nop 0
	v_pk_add_f32 v[110:111], v[110:111], 1.0 op_sel_hi:[1,0]
	s_nop 0
	v_rcp_f32_e32 v110, v110
	v_rcp_f32_e32 v111, v111
	s_nop 0
	v_pk_mul_f32 v[110:111], v[110:111], v[132:133]
	s_nop 0
	v_pk_mul_f32 v[112:113], v[110:111], s[82:83] op_sel_hi:[1,0]
	v_cvt_f16_f32_e32 v110, v110
	v_exp_f32_e32 v112, v112
	v_exp_f32_e32 v113, v113
	s_nop 0
	v_pk_add_f32 v[112:113], v[112:113], 1.0 op_sel_hi:[1,0] neg_lo:[1,0] neg_hi:[1,0]
	s_nop 0
	v_max_f32_e32 v113, 0, v113
	v_max_f32_e32 v112, 0, v112
	v_sqrt_f32_e32 v112, v112
	v_sqrt_f32_e32 v113, v113
	s_nop 0
	v_pk_mul_f32 v[108:109], v[108:109], v[112:113]
	s_nop 0
	v_pk_mul_f32 v[108:109], v[108:109], v[118:119]
	s_nop 0
	v_cvt_f16_f32_sdwa v108, v108 dst_sel:WORD_1 dst_unused:UNUSED_PAD src0_sel:DWORD
	v_cvt_f16_f32_sdwa v109, v109 dst_sel:WORD_1 dst_unused:UNUSED_PAD src0_sel:DWORD
	v_or_b32_e32 v108, v108, v110
	v_cvt_f16_f32_e32 v110, v111
	v_or_b32_e32 v109, v109, v110
	v_lshl_add_u64 v[110:111], v[116:117], 2, s[20:21]
	global_store_dwordx4 v[110:111], v[106:109], off
	v_pk_mul_f32 v[116:117], v[102:103], s[82:83] op_sel_hi:[1,0]
	v_cvt_f16_f32_e32 v102, v102
	v_lshl_add_u64 v[106:107], v[138:139], 0, s[6:7]
	v_lshl_add_u64 v[108:109], v[106:107], 0, v[152:153]
	v_exp_f32_e32 v116, v116
	v_exp_f32_e32 v117, v117
	s_mov_b64 s[6:7], 0x24000
	v_pk_add_f32 v[116:117], v[116:117], 1.0 op_sel_hi:[1,0] neg_lo:[1,0] neg_hi:[1,0]
	s_nop 0
	v_max_f32_e32 v117, 0, v117
	v_max_f32_e32 v116, 0, v116
	v_sqrt_f32_e32 v116, v116
	v_sqrt_f32_e32 v117, v117
	s_waitcnt vmcnt(11) lgkmcnt(0)
	v_lshlrev_b32_e32 v112, 16, v230
	v_and_b32_e32 v113, 0xffff0000, v230
	v_pk_mul_f32 v[98:99], v[98:99], v[116:117]
	v_lshlrev_b32_e32 v110, 16, v231
	v_pk_mul_f32 v[98:99], v[98:99], v[112:113]
	v_and_b32_e32 v111, 0xffff0000, v231
	v_add_u32_e32 v239, 0x40008, v238
	global_load_dwordx2 v[230:231], v239, s[8:9]
	v_cvt_f16_f32_sdwa v98, v98 dst_sel:WORD_1 dst_unused:UNUSED_PAD src0_sel:DWORD
	v_cvt_f16_f32_sdwa v99, v99 dst_sel:WORD_1 dst_unused:UNUSED_PAD src0_sel:DWORD
	v_or_b32_e32 v98, v98, v102
	v_cvt_f16_f32_e32 v102, v103
	v_or_b32_e32 v99, v99, v102
	v_pk_mul_f32 v[102:103], v[104:105], s[88:89] op_sel_hi:[1,0]
	s_nop 0
	v_exp_f32_e32 v102, v102
	v_exp_f32_e32 v103, v103
	s_nop 0
	v_pk_add_f32 v[102:103], v[102:103], 1.0 op_sel_hi:[1,0]
	s_nop 0
	v_rcp_f32_e32 v102, v102
	v_rcp_f32_e32 v103, v103
	s_nop 0
	v_pk_mul_f32 v[102:103], v[102:103], v[132:133]
	s_nop 0
	v_pk_mul_f32 v[104:105], v[102:103], s[82:83] op_sel_hi:[1,0]
	v_cvt_f16_f32_e32 v102, v102
	v_exp_f32_e32 v104, v104
	v_exp_f32_e32 v105, v105
	s_nop 0
	v_pk_add_f32 v[104:105], v[104:105], 1.0 op_sel_hi:[1,0] neg_lo:[1,0] neg_hi:[1,0]
	s_nop 0
	v_max_f32_e32 v105, 0, v105
	v_max_f32_e32 v104, 0, v104
	v_sqrt_f32_e32 v104, v104
	v_sqrt_f32_e32 v105, v105
	s_nop 0
	v_pk_mul_f32 v[100:101], v[100:101], v[104:105]
	s_nop 0
	v_pk_mul_f32 v[100:101], v[100:101], v[110:111]
	s_nop 0
	v_cvt_f16_f32_sdwa v100, v100 dst_sel:WORD_1 dst_unused:UNUSED_PAD src0_sel:DWORD
	v_cvt_f16_f32_sdwa v101, v101 dst_sel:WORD_1 dst_unused:UNUSED_PAD src0_sel:DWORD
	v_or_b32_e32 v100, v100, v102
	v_cvt_f16_f32_e32 v102, v103
	v_or_b32_e32 v101, v101, v102
	v_lshl_add_u64 v[102:103], v[108:109], 2, s[20:21]
	global_store_dwordx4 v[102:103], v[98:101], off
	v_pk_mul_f32 v[108:109], v[94:95], s[82:83] op_sel_hi:[1,0]
	v_cvt_f16_f32_e32 v94, v94
	v_lshl_add_u64 v[98:99], v[138:139], 0, s[6:7]
	v_lshl_add_u64 v[100:101], v[98:99], 0, v[152:153]
	v_exp_f32_e32 v108, v108
	v_exp_f32_e32 v109, v109
	s_mov_b64 s[6:7], 0x28000
	v_pk_add_f32 v[108:109], v[108:109], 1.0 op_sel_hi:[1,0] neg_lo:[1,0] neg_hi:[1,0]
	s_nop 0
	v_max_f32_e32 v109, 0, v109
	v_max_f32_e32 v108, 0, v108
	v_sqrt_f32_e32 v108, v108
	v_sqrt_f32_e32 v109, v109
	s_waitcnt vmcnt(12) lgkmcnt(0)
; __device__ __forceinline__ float bf_lo(unsigned w) { return __uint_as_float(w << 16); }
; __device__ __forceinline__ float bf_hi(unsigned w) { return __uint_as_float(w & 0xffff0000u); }
;     __device__ __forceinline__ void operator()(const f32x4 (&acc)[2][2][4][2], const Unit& u, int wr, int wc, int fr, int fq) const {
;     ...
;             const f32x4 lv = *(const f32x4*)(lam + c0 + 4 * hf), bav = *(const f32x4*)(b_a + c0 + 4 * hf), biv = *(const f32x4*)(b_i + c0 + 4 * hf);
;             f32x4 sp;
; #pragma unroll
;             for (int j = 0; j < 4; ++j) sp[j] = 8.0f * softplus_neg(lv[j]);
;     ...
;                     const int row = row0 + ai * HALF + m * 16; const size_t off = (size_t)row * D + c0 + 4 * hf;
;                     const u32x2 xw = *(const u32x2*)(xrc + off); const float xr[4] = {bf_lo(xw.x), bf_hi(xw.x), bf_lo(xw.y), bf_hi(xw.y)};
;                     u32x4 w;
; #pragma unroll
;                     for (int j2 = 0; j2 < 2; ++j2) { const int j = 2 * j2;
;                         const f32x2v rp = (f32x2v){acc[ai][0][m][hf][j], acc[ai][0][m][hf][j + 1]} + (f32x2v){bav[j], bav[j + 1]}, ip = (f32x2v){acc[ai][1][m][hf][j], acc[ai][1][m][hf][j + 1]} + (f32x2v){biv[j], biv[j + 1]};
;                         const f32x2v er = rp * (-1.4426950408889634f), ei = ip * (-1.4426950408889634f);
;                         f32x2v tr, ti; tr.x = __builtin_amdgcn_exp2f(er.x); tr.y = __builtin_amdgcn_exp2f(er.y); ti.x = __builtin_amdgcn_exp2f(ei.x); ti.y = __builtin_amdgcn_exp2f(ei.y);
;                         const f32x2v dr = tr + 1.0f, di = ti + 1.0f; f32x2v r, ig; r.x = __builtin_amdgcn_rcpf(dr.x); r.y = __builtin_amdgcn_rcpf(dr.y); ig.x = __builtin_amdgcn_rcpf(di.x); ig.y = __builtin_amdgcn_rcpf(di.y);
;                         const f32x2v la = r * (f32x2v){-sp[j], -sp[j + 1]}, e2 = la * 2.8853900817779268f;
;                         f32x2v a2; a2.x = __builtin_amdgcn_exp2f(e2.x); a2.y = __builtin_amdgcn_exp2f(e2.y);
;                         const f32x2v om = __builtin_elementwise_max(1.0f - a2, (f32x2v){0.f, 0.f}); f32x2v mult; mult.x = __builtin_amdgcn_sqrtf(om.x); mult.y = __builtin_amdgcn_sqrtf(om.y);
;                         const f32x2v bt = (mult * ig) * (f32x2v){xr[j], xr[j + 1]};
;                         w[j] = pack_f16(la.x, bt.x); w[j + 1] = pack_f16(la.y, bt.y); }
;                     *(u32x4*)(AB + off) = w;
	v_lshlrev_b32_e32 v104, 16, v232
	v_and_b32_e32 v105, 0xffff0000, v232
	v_pk_mul_f32 v[90:91], v[90:91], v[108:109]
	v_lshlrev_b32_e32 v102, 16, v233
	v_pk_mul_f32 v[90:91], v[90:91], v[104:105]
	v_and_b32_e32 v103, 0xffff0000, v233
	v_add_u32_e32 v239, 0x48008, v238
	global_load_dwordx2 v[232:233], v239, s[8:9]
	v_cvt_f16_f32_sdwa v90, v90 dst_sel:WORD_1 dst_unused:UNUSED_PAD src0_sel:DWORD
	v_cvt_f16_f32_sdwa v91, v91 dst_sel:WORD_1 dst_unused:UNUSED_PAD src0_sel:DWORD
	v_or_b32_e32 v90, v90, v94
	v_cvt_f16_f32_e32 v94, v95
	v_or_b32_e32 v91, v91, v94
	v_pk_mul_f32 v[94:95], v[96:97], s[88:89] op_sel_hi:[1,0]
	s_nop 0
	v_exp_f32_e32 v94, v94
	v_exp_f32_e32 v95, v95
	s_nop 0
	v_pk_add_f32 v[94:95], v[94:95], 1.0 op_sel_hi:[1,0]
	s_nop 0
	v_rcp_f32_e32 v94, v94
	v_rcp_f32_e32 v95, v95
	s_nop 0
	v_pk_mul_f32 v[94:95], v[94:95], v[132:133]
	s_nop 0
	v_pk_mul_f32 v[96:97], v[94:95], s[82:83] op_sel_hi:[1,0]
	v_cvt_f16_f32_e32 v94, v94
	v_exp_f32_e32 v96, v96
	v_exp_f32_e32 v97, v97
	s_nop 0
	v_pk_add_f32 v[96:97], v[96:97], 1.0 op_sel_hi:[1,0] neg_lo:[1,0] neg_hi:[1,0]
	s_nop 0
	v_max_f32_e32 v97, 0, v97
	v_max_f32_e32 v96, 0, v96
	v_sqrt_f32_e32 v96, v96
	v_sqrt_f32_e32 v97, v97
	s_nop 0
	v_pk_mul_f32 v[92:93], v[92:93], v[96:97]
	s_nop 0
	v_pk_mul_f32 v[92:93], v[92:93], v[102:103]
	s_nop 0
	v_cvt_f16_f32_sdwa v92, v92 dst_sel:WORD_1 dst_unused:UNUSED_PAD src0_sel:DWORD
	v_cvt_f16_f32_sdwa v93, v93 dst_sel:WORD_1 dst_unused:UNUSED_PAD src0_sel:DWORD
	v_or_b32_e32 v92, v92, v94
	v_cvt_f16_f32_e32 v94, v95
	v_or_b32_e32 v93, v93, v94
	v_lshl_add_u64 v[94:95], v[100:101], 2, s[20:21]
	global_store_dwordx4 v[94:95], v[90:93], off
	v_pk_mul_f32 v[100:101], v[78:79], s[82:83] op_sel_hi:[1,0]
	v_cvt_f16_f32_e32 v78, v78
	v_lshl_add_u64 v[90:91], v[138:139], 0, s[6:7]
	v_lshl_add_u64 v[92:93], v[90:91], 0, v[152:153]
	v_exp_f32_e32 v100, v100
	v_exp_f32_e32 v101, v101
	s_mov_b64 s[6:7], 0x2c000
	v_pk_add_f32 v[100:101], v[100:101], 1.0 op_sel_hi:[1,0] neg_lo:[1,0] neg_hi:[1,0]
	s_nop 0
	v_max_f32_e32 v101, 0, v101
	v_max_f32_e32 v100, 0, v100
	v_sqrt_f32_e32 v100, v100
	v_sqrt_f32_e32 v101, v101
	s_waitcnt vmcnt(13) lgkmcnt(0)
	v_lshlrev_b32_e32 v96, 16, v234
	v_and_b32_e32 v97, 0xffff0000, v234
	v_pk_mul_f32 v[74:75], v[74:75], v[100:101]
	v_lshlrev_b32_e32 v94, 16, v235
	v_pk_mul_f32 v[74:75], v[74:75], v[96:97]
	v_and_b32_e32 v95, 0xffff0000, v235
	v_add_u32_e32 v239, 0x50008, v238
	global_load_dwordx2 v[234:235], v239, s[8:9]
	v_cvt_f16_f32_sdwa v74, v74 dst_sel:WORD_1 dst_unused:UNUSED_PAD src0_sel:DWORD
	v_cvt_f16_f32_sdwa v75, v75 dst_sel:WORD_1 dst_unused:UNUSED_PAD src0_sel:DWORD
	v_or_b32_e32 v74, v74, v78
	v_cvt_f16_f32_e32 v78, v79
	v_or_b32_e32 v75, v75, v78
	v_pk_mul_f32 v[78:79], v[80:81], s[88:89] op_sel_hi:[1,0]
	s_nop 0
	v_exp_f32_e32 v78, v78
	v_exp_f32_e32 v79, v79
	s_nop 0
	v_pk_add_f32 v[78:79], v[78:79], 1.0 op_sel_hi:[1,0]
	s_nop 0
	v_rcp_f32_e32 v78, v78
	v_rcp_f32_e32 v79, v79
	s_nop 0
	v_pk_mul_f32 v[78:79], v[78:79], v[132:133]
	s_nop 0
	v_pk_mul_f32 v[80:81], v[78:79], s[82:83] op_sel_hi:[1,0]
	v_cvt_f16_f32_e32 v78, v78
	v_exp_f32_e32 v80, v80
	v_exp_f32_e32 v81, v81
	s_nop 0
	v_pk_add_f32 v[80:81], v[80:81], 1.0 op_sel_hi:[1,0] neg_lo:[1,0] neg_hi:[1,0]
	s_nop 0
	v_max_f32_e32 v81, 0, v81
	v_max_f32_e32 v80, 0, v80
	v_sqrt_f32_e32 v80, v80
	v_sqrt_f32_e32 v81, v81
	s_nop 0
	v_pk_mul_f32 v[76:77], v[76:77], v[80:81]
	s_nop 0
	v_pk_mul_f32 v[76:77], v[76:77], v[94:95]
	s_nop 0
	v_cvt_f16_f32_sdwa v76, v76 dst_sel:WORD_1 dst_unused:UNUSED_PAD src0_sel:DWORD
	v_cvt_f16_f32_sdwa v77, v77 dst_sel:WORD_1 dst_unused:UNUSED_PAD src0_sel:DWORD
	v_or_b32_e32 v76, v76, v78
	v_cvt_f16_f32_e32 v78, v79
	v_or_b32_e32 v77, v77, v78
	v_lshl_add_u64 v[78:79], v[92:93], 2, s[20:21]
	global_store_dwordx4 v[78:79], v[74:77], off
	v_lshl_add_u64 v[78:79], v[138:139], 0, s[6:7]
	s_nop 0
	v_lshl_add_u64 v[74:75], v[78:79], 0, v[152:153]
	s_waitcnt vmcnt(14) lgkmcnt(0)
	v_lshlrev_b32_e32 v80, 16, v236
	v_and_b32_e32 v81, 0xffff0000, v236
	v_pk_mul_f32 v[66:67], v[66:67], v[80:81]
	v_lshlrev_b32_e32 v76, 16, v237
	v_cvt_f16_f32_sdwa v66, v66 dst_sel:WORD_1 dst_unused:UNUSED_PAD src0_sel:DWORD
	v_cvt_f16_f32_sdwa v67, v67 dst_sel:WORD_1 dst_unused:UNUSED_PAD src0_sel:DWORD
	v_and_b32_e32 v77, 0xffff0000, v237
	v_add_u32_e32 v239, 0x58008, v238
	global_load_dwordx2 v[236:237], v239, s[8:9]
	v_or_b32_e32 v66, v66, v70
	v_cvt_f16_f32_e32 v70, v71
	v_or_b32_e32 v67, v67, v70
	v_pk_mul_f32 v[70:71], v[72:73], s[88:89] op_sel_hi:[1,0]
	s_nop 0
	v_exp_f32_e32 v70, v70
	v_exp_f32_e32 v71, v71
	s_nop 0
	v_pk_add_f32 v[70:71], v[70:71], 1.0 op_sel_hi:[1,0]
	s_nop 0
	v_rcp_f32_e32 v70, v70
	v_rcp_f32_e32 v71, v71
	s_nop 0
	v_pk_mul_f32 v[70:71], v[70:71], v[132:133]
	s_nop 0
	v_pk_mul_f32 v[72:73], v[70:71], s[82:83] op_sel_hi:[1,0]
	v_cvt_f16_f32_e32 v70, v70
	v_exp_f32_e32 v72, v72
	v_exp_f32_e32 v73, v73
	s_nop 0
	v_pk_add_f32 v[72:73], v[72:73], 1.0 op_sel_hi:[1,0] neg_lo:[1,0] neg_hi:[1,0]
	s_nop 0
	v_max_f32_e32 v73, 0, v73
	v_max_f32_e32 v72, 0, v72
	v_sqrt_f32_e32 v72, v72
	v_sqrt_f32_e32 v73, v73
	s_nop 0
	v_pk_mul_f32 v[68:69], v[68:69], v[72:73]
	s_nop 0
	v_pk_mul_f32 v[68:69], v[68:69], v[76:77]
	s_nop 0
	v_cvt_f16_f32_sdwa v68, v68 dst_sel:WORD_1 dst_unused:UNUSED_PAD src0_sel:DWORD
	v_cvt_f16_f32_sdwa v69, v69 dst_sel:WORD_1 dst_unused:UNUSED_PAD src0_sel:DWORD
	v_or_b32_e32 v68, v68, v70
	v_cvt_f16_f32_e32 v70, v71
	v_or_b32_e32 v69, v69, v70
	v_lshl_add_u64 v[70:71], v[74:75], 2, s[20:21]
	global_store_dwordx4 v[70:71], v[66:69], off
	global_load_dwordx4 v[74:77], v[154:155], off offset:16
	global_load_dwordx4 v[70:73], v[156:157], off offset:16
	global_load_dwordx4 v[66:69], v[158:159], off offset:16
	s_waitcnt vmcnt(0)
	v_mul_f32_e32 v74, 0xbfb8aa3b, v74
	v_exp_f32_e32 v74, v74
	s_nop 0
	v_cmp_ngt_f32_e32 vcc, s64, v74
	s_and_saveexec_b64 s[0:1], vcc
	s_xor_b64 s[36:37], exec, s[0:1]
	s_cbranch_execz .LBB0_207
	v_add_f32_e32 v74, 1.0, v74
	v_cmp_gt_f32_e32 vcc, s60, v74
	s_nop 1
	v_cndmask_b32_e64 v80, 0, 32, vcc
	v_ldexp_f32 v74, v74, v80
	v_log_f32_e32 v74, v74
	s_nop 0
	v_mul_f32_e32 v80, 0x3f317217, v74
	v_fma_f32 v80, v74, s65, -v80
	v_fmac_f32_e32 v80, 0x3377d1cf, v74
	v_fmac_f32_e32 v80, 0x3f317217, v74
	v_cmp_lt_f32_e64 s[6:7], |v74|, s66
	s_nop 1
	v_cndmask_b32_e64 v74, v74, v80, s[6:7]
	v_cndmask_b32_e32 v80, 0, v252, vcc
	v_sub_f32_e32 v80, v74, v80

; __device__ __forceinline__ unsigned pack_f16(float lo, float hi) { const _Float16 a = (_Float16)lo, b = (_Float16)hi; return (unsigned)__builtin_bit_cast(unsigned short, a) | ((unsigned)__builtin_bit_cast(unsigned short, b) << 16); }
;     __device__ __forceinline__ void operator()(const f32x4 (&acc)[2][2][4][2], const Unit& u, int wr, int wc, int fr, int fq) const {
;     ...
;                     for (int j2 = 0; j2 < 2; ++j2) { const int j = 2 * j2;
;                         const f32x2v rp = (f32x2v){acc[ai][0][m][hf][j], acc[ai][0][m][hf][j + 1]} + (f32x2v){bav[j], bav[j + 1]}, ip = (f32x2v){acc[ai][1][m][hf][j], acc[ai][1][m][hf][j + 1]} + (f32x2v){biv[j], biv[j + 1]};
;                         const f32x2v er = rp * (-1.4426950408889634f), ei = ip * (-1.4426950408889634f);
;                         f32x2v tr, ti; tr.x = __builtin_amdgcn_exp2f(er.x); tr.y = __builtin_amdgcn_exp2f(er.y); ti.x = __builtin_amdgcn_exp2f(ei.x); ti.y = __builtin_amdgcn_exp2f(ei.y);
;                         const f32x2v dr = tr + 1.0f, di = ti + 1.0f; f32x2v r, ig; r.x = __builtin_amdgcn_rcpf(dr.x); r.y = __builtin_amdgcn_rcpf(dr.y); ig.x = __builtin_amdgcn_rcpf(di.x); ig.y = __builtin_amdgcn_rcpf(di.y);
;                         const f32x2v la = r * (f32x2v){-sp[j], -sp[j + 1]}, e2 = la * 2.8853900817779268f;
;                         f32x2v a2; a2.x = __builtin_amdgcn_exp2f(e2.x); a2.y = __builtin_amdgcn_exp2f(e2.y);
;                         const f32x2v om = __builtin_elementwise_max(1.0f - a2, (f32x2v){0.f, 0.f}); f32x2v mult; mult.x = __builtin_amdgcn_sqrtf(om.x); mult.y = __builtin_amdgcn_sqrtf(om.y);
;                         const f32x2v bt = (mult * ig) * (f32x2v){xr[j], xr[j + 1]};
;                         w[j] = pack_f16(la.x, bt.x); w[j + 1] = pack_f16(la.y, bt.y); }
;                     *(u32x4*)(AB + off) = w;
.LBB0_219:
	s_andn2_saveexec_b64 s[0:1], s[36:37]
	v_fmamk_f32 v75, v76, 0xbe800000, v249
	v_fma_f32 v75, -v76, v75, 0.5
	v_fma_f32 v75, -v76, v75, 1.0
	v_mul_f32_e32 v75, v76, v75
	s_or_b64 exec, exec, s[0:1]
	v_or_b32_e32 v152, 4, v152
	v_lshl_add_u64 v[76:77], v[152:153], 0, v[138:139]
	v_pk_add_f32 v[62:63], v[62:63], v[70:71]
	v_pk_add_f32 v[58:59], v[58:59], v[66:67]
	v_pk_mul_f32 v[62:63], v[62:63], s[88:89] op_sel_hi:[1,0]
	v_pk_mul_f32 v[58:59], v[58:59], s[88:89] op_sel_hi:[1,0]
	v_exp_f32_e32 v62, v62
	v_exp_f32_e32 v63, v63
	v_exp_f32_e32 v58, v58
	v_exp_f32_e32 v59, v59
	s_mov_b32 s0, 0xc1000000
	v_pk_add_f32 v[62:63], v[62:63], 1.0 op_sel_hi:[1,0]
	v_pk_add_f32 v[64:65], v[64:65], v[72:73]
	v_rcp_f32_e32 v62, v62
	v_rcp_f32_e32 v63, v63
	v_pk_add_f32 v[58:59], v[58:59], 1.0 op_sel_hi:[1,0]
	v_pk_mul_f32 v[64:65], v[64:65], s[88:89] op_sel_hi:[1,0]
	v_rcp_f32_e32 v86, v58
	v_rcp_f32_e32 v87, v59
	v_pk_mul_f32 v[58:59], v[80:81], s[0:1] op_sel_hi:[1,0]
	v_exp_f32_e32 v64, v64
	v_pk_mul_f32 v[62:63], v[62:63], v[58:59]
	v_exp_f32_e32 v65, v65
	v_pk_mul_f32 v[80:81], v[62:63], s[82:83] op_sel_hi:[1,0]
	v_cvt_f16_f32_e32 v62, v62
	v_exp_f32_e32 v80, v80
	v_exp_f32_e32 v81, v81
	v_pk_add_f32 v[60:61], v[60:61], v[68:69]
	v_cvt_f16_f32_e32 v63, v63
	v_pk_mul_f32 v[60:61], v[60:61], s[88:89] op_sel_hi:[1,0]
	v_pk_add_f32 v[80:81], v[80:81], 1.0 op_sel_hi:[1,0] neg_lo:[1,0] neg_hi:[1,0]
	v_exp_f32_e32 v60, v60
	v_max_f32_e32 v81, 0, v81
	v_max_f32_e32 v80, 0, v80
	v_sqrt_f32_e32 v80, v80
	v_sqrt_f32_e32 v81, v81
	v_exp_f32_e32 v61, v61
	v_pk_add_f32 v[64:65], v[64:65], 1.0 op_sel_hi:[1,0]
	v_pk_add_f32 v[54:55], v[54:55], v[70:71]
	v_pk_mul_f32 v[80:81], v[86:87], v[80:81]
	v_rcp_f32_e32 v64, v64
	v_rcp_f32_e32 v65, v65
	v_pk_add_f32 v[60:61], v[60:61], 1.0 op_sel_hi:[1,0]
	v_pk_mul_f32 v[54:55], v[54:55], s[88:89] op_sel_hi:[1,0]
	v_pk_add_f32 v[50:51], v[50:51], v[66:67]
	v_exp_f32_e32 v54, v54
	v_exp_f32_e32 v55, v55
	v_pk_mul_f32 v[50:51], v[50:51], s[88:89] op_sel_hi:[1,0]
	v_pk_add_f32 v[56:57], v[56:57], v[72:73]
	v_exp_f32_e32 v50, v50
	v_pk_add_f32 v[54:55], v[54:55], 1.0 op_sel_hi:[1,0]
	v_exp_f32_e32 v51, v51
	v_rcp_f32_e32 v54, v54
	v_rcp_f32_e32 v55, v55
	v_pk_add_f32 v[52:53], v[52:53], v[68:69]
	v_pk_add_f32 v[50:51], v[50:51], 1.0 op_sel_hi:[1,0]
	v_pk_mul_f32 v[52:53], v[52:53], s[88:89] op_sel_hi:[1,0]
	v_pk_mul_f32 v[54:55], v[54:55], v[58:59]
	v_rcp_f32_e32 v50, v50
	v_rcp_f32_e32 v51, v51
	v_exp_f32_e32 v52, v52
	v_exp_f32_e32 v53, v53
	v_pk_add_f32 v[46:47], v[46:47], v[70:71]
	v_pk_add_f32 v[42:43], v[42:43], v[66:67]
	v_pk_mul_f32 v[46:47], v[46:47], s[88:89] op_sel_hi:[1,0]
	v_pk_add_f32 v[52:53], v[52:53], 1.0 op_sel_hi:[1,0]
	v_exp_f32_e32 v46, v46
	v_rcp_f32_e32 v52, v52
	v_rcp_f32_e32 v53, v53
	v_exp_f32_e32 v47, v47
	v_pk_mul_f32 v[42:43], v[42:43], s[88:89] op_sel_hi:[1,0]
	v_pk_add_f32 v[48:49], v[48:49], v[72:73]
	v_exp_f32_e32 v42, v42
	v_pk_add_f32 v[46:47], v[46:47], 1.0 op_sel_hi:[1,0]
	v_exp_f32_e32 v43, v43
	v_rcp_f32_e32 v46, v46
	v_rcp_f32_e32 v47, v47
	v_pk_add_f32 v[44:45], v[44:45], v[68:69]
	v_pk_add_f32 v[42:43], v[42:43], 1.0 op_sel_hi:[1,0]
	v_pk_mul_f32 v[44:45], v[44:45], s[88:89] op_sel_hi:[1,0]
	v_pk_mul_f32 v[46:47], v[46:47], v[58:59]
	s_waitcnt lgkmcnt(0)
	v_lshlrev_b32_e32 v84, 16, v222
	v_and_b32_e32 v85, 0xffff0000, v222
	v_pk_mul_f32 v[80:81], v[80:81], v[84:85]
	v_lshlrev_b32_e32 v82, 16, v223
	v_cvt_f16_f32_sdwa v80, v80 dst_sel:WORD_1 dst_unused:UNUSED_PAD src0_sel:DWORD
	v_and_b32_e32 v83, 0xffff0000, v223
	v_rcp_f32_e32 v42, v42
	v_rcp_f32_e32 v43, v43
	v_or_b32_e32 v62, v80, v62
	v_cvt_f16_f32_sdwa v80, v81 dst_sel:WORD_1 dst_unused:UNUSED_PAD src0_sel:DWORD
	v_rcp_f32_e32 v81, v61
	v_exp_f32_e32 v44, v44
	v_exp_f32_e32 v45, v45
	v_or_b32_e32 v63, v80, v63
	v_rcp_f32_e32 v80, v60
	v_pk_mul_f32 v[60:61], v[74:75], s[0:1] op_sel_hi:[1,0]
	v_pk_add_f32 v[44:45], v[44:45], 1.0 op_sel_hi:[1,0]
	v_pk_mul_f32 v[64:65], v[64:65], v[60:61]
	v_rcp_f32_e32 v44, v44
	v_pk_mul_f32 v[74:75], v[64:65], s[82:83] op_sel_hi:[1,0]
	v_cvt_f16_f32_e32 v64, v64
	v_exp_f32_e32 v74, v74
	v_exp_f32_e32 v75, v75
	v_cvt_f16_f32_e32 v65, v65
	v_rcp_f32_e32 v45, v45
	v_pk_add_f32 v[38:39], v[38:39], v[70:71]
	v_pk_add_f32 v[74:75], v[74:75], 1.0 op_sel_hi:[1,0] neg_lo:[1,0] neg_hi:[1,0]
	v_pk_mul_f32 v[38:39], v[38:39], s[88:89] op_sel_hi:[1,0]
	v_max_f32_e32 v75, 0, v75
	v_max_f32_e32 v74, 0, v74
	v_sqrt_f32_e32 v74, v74
	v_sqrt_f32_e32 v75, v75
	v_exp_f32_e32 v38, v38
	v_exp_f32_e32 v39, v39
	v_pk_add_f32 v[34:35], v[34:35], v[66:67]
	v_pk_mul_f32 v[74:75], v[80:81], v[74:75]
	v_pk_mul_f32 v[34:35], v[34:35], s[88:89] op_sel_hi:[1,0]
	v_pk_mul_f32 v[74:75], v[74:75], v[82:83]
	v_pk_add_f32 v[38:39], v[38:39], 1.0 op_sel_hi:[1,0]
	v_cvt_f16_f32_sdwa v74, v74 dst_sel:WORD_1 dst_unused:UNUSED_PAD src0_sel:DWORD
	v_rcp_f32_e32 v38, v38
	v_rcp_f32_e32 v39, v39
	v_exp_f32_e32 v34, v34
	v_or_b32_e32 v64, v74, v64
	v_cvt_f16_f32_sdwa v74, v75 dst_sel:WORD_1 dst_unused:UNUSED_PAD src0_sel:DWORD
	v_pk_mul_f32 v[38:39], v[38:39], v[58:59]
	v_exp_f32_e32 v35, v35
	v_pk_add_f32 v[40:41], v[40:41], v[72:73]
	v_or_b32_e32 v65, v74, v65
	v_lshl_add_u64 v[74:75], v[76:77], 2, s[20:21]
	global_store_dwordx4 v[74:75], v[62:65], off
	v_pk_mul_f32 v[76:77], v[54:55], s[82:83] op_sel_hi:[1,0]
	v_cvt_f16_f32_e32 v54, v54
	v_lshl_add_u64 v[62:63], v[130:131], 0, v[152:153]
	v_exp_f32_e32 v76, v76
	v_exp_f32_e32 v77, v77
	v_pk_add_f32 v[34:35], v[34:35], 1.0 op_sel_hi:[1,0]
	v_pk_add_f32 v[36:37], v[36:37], v[68:69]
	v_rcp_f32_e32 v34, v34
	v_pk_add_f32 v[76:77], v[76:77], 1.0 op_sel_hi:[1,0] neg_lo:[1,0] neg_hi:[1,0]
; __device__ __forceinline__ unsigned pack_f16(float lo, float hi) { const _Float16 a = (_Float16)lo, b = (_Float16)hi; return (unsigned)__builtin_bit_cast(unsigned short, a) | ((unsigned)__builtin_bit_cast(unsigned short, b) << 16); }
;     __device__ __forceinline__ void operator()(const f32x4 (&acc)[2][2][4][2], const Unit& u, int wr, int wc, int fr, int fq) const {
;     ...
;                     for (int j2 = 0; j2 < 2; ++j2) { const int j = 2 * j2;
;                         const f32x2v rp = (f32x2v){acc[ai][0][m][hf][j], acc[ai][0][m][hf][j + 1]} + (f32x2v){bav[j], bav[j + 1]}, ip = (f32x2v){acc[ai][1][m][hf][j], acc[ai][1][m][hf][j + 1]} + (f32x2v){biv[j], biv[j + 1]};
;                         const f32x2v er = rp * (-1.4426950408889634f), ei = ip * (-1.4426950408889634f);
;                         f32x2v tr, ti; tr.x = __builtin_amdgcn_exp2f(er.x); tr.y = __builtin_amdgcn_exp2f(er.y); ti.x = __builtin_amdgcn_exp2f(ei.x); ti.y = __builtin_amdgcn_exp2f(ei.y);
;                         const f32x2v dr = tr + 1.0f, di = ti + 1.0f; f32x2v r, ig; r.x = __builtin_amdgcn_rcpf(dr.x); r.y = __builtin_amdgcn_rcpf(dr.y); ig.x = __builtin_amdgcn_rcpf(di.x); ig.y = __builtin_amdgcn_rcpf(di.y);
;                         const f32x2v la = r * (f32x2v){-sp[j], -sp[j + 1]}, e2 = la * 2.8853900817779268f;
;                         f32x2v a2; a2.x = __builtin_amdgcn_exp2f(e2.x); a2.y = __builtin_amdgcn_exp2f(e2.y);
;                         const f32x2v om = __builtin_elementwise_max(1.0f - a2, (f32x2v){0.f, 0.f}); f32x2v mult; mult.x = __builtin_amdgcn_sqrtf(om.x); mult.y = __builtin_amdgcn_sqrtf(om.y);
;                         const f32x2v bt = (mult * ig) * (f32x2v){xr[j], xr[j + 1]};
;                         w[j] = pack_f16(la.x, bt.x); w[j + 1] = pack_f16(la.y, bt.y); }
;                     *(u32x4*)(AB + off) = w;
	v_rcp_f32_e32 v35, v35
	v_max_f32_e32 v77, 0, v77
	v_max_f32_e32 v76, 0, v76
	v_sqrt_f32_e32 v76, v76
	v_sqrt_f32_e32 v77, v77
	v_pk_mul_f32 v[36:37], v[36:37], s[88:89] op_sel_hi:[1,0]
	v_pk_add_f32 v[30:31], v[30:31], v[70:71]
	v_exp_f32_e32 v36, v36
	v_pk_mul_f32 v[50:51], v[50:51], v[76:77]
	v_exp_f32_e32 v37, v37
	v_pk_mul_f32 v[30:31], v[30:31], s[88:89] op_sel_hi:[1,0]
	v_pk_add_f32 v[26:27], v[26:27], v[66:67]
	v_exp_f32_e32 v30, v30
	v_pk_add_f32 v[36:37], v[36:37], 1.0 op_sel_hi:[1,0]
	v_exp_f32_e32 v31, v31
	v_rcp_f32_e32 v36, v36
	v_rcp_f32_e32 v37, v37
	v_pk_mul_f32 v[26:27], v[26:27], s[88:89] op_sel_hi:[1,0]
	v_pk_add_f32 v[30:31], v[30:31], 1.0 op_sel_hi:[1,0]
	v_exp_f32_e32 v26, v26
	v_rcp_f32_e32 v30, v30
	v_rcp_f32_e32 v31, v31
	v_exp_f32_e32 v27, v27
	v_pk_add_f32 v[32:33], v[32:33], v[72:73]
	v_pk_add_f32 v[28:29], v[28:29], v[68:69]
	v_pk_mul_f32 v[30:31], v[30:31], v[58:59]
	v_pk_add_f32 v[26:27], v[26:27], 1.0 op_sel_hi:[1,0]
	v_pk_mul_f32 v[28:29], v[28:29], s[88:89] op_sel_hi:[1,0]
	v_rcp_f32_e32 v26, v26
	v_rcp_f32_e32 v27, v27
	v_exp_f32_e32 v28, v28
	v_exp_f32_e32 v29, v29
	v_pk_add_f32 v[22:23], v[22:23], v[70:71]
	v_pk_add_f32 v[18:19], v[18:19], v[66:67]
	v_pk_mul_f32 v[22:23], v[22:23], s[88:89] op_sel_hi:[1,0]
	v_pk_add_f32 v[28:29], v[28:29], 1.0 op_sel_hi:[1,0]
	v_exp_f32_e32 v22, v22
	v_rcp_f32_e32 v28, v28
	v_rcp_f32_e32 v29, v29
	v_exp_f32_e32 v23, v23
	v_pk_mul_f32 v[18:19], v[18:19], s[88:89] op_sel_hi:[1,0]
	v_pk_add_f32 v[24:25], v[24:25], v[72:73]
	v_exp_f32_e32 v18, v18
	v_pk_add_f32 v[22:23], v[22:23], 1.0 op_sel_hi:[1,0]
	v_exp_f32_e32 v19, v19
	v_rcp_f32_e32 v22, v22
	v_rcp_f32_e32 v23, v23
	v_pk_add_f32 v[20:21], v[20:21], v[68:69]
	v_pk_add_f32 v[18:19], v[18:19], 1.0 op_sel_hi:[1,0]
	v_pk_mul_f32 v[20:21], v[20:21], s[88:89] op_sel_hi:[1,0]
	v_pk_mul_f32 v[22:23], v[22:23], v[58:59]
	v_rcp_f32_e32 v18, v18
	v_rcp_f32_e32 v19, v19
	v_exp_f32_e32 v20, v20
	v_exp_f32_e32 v21, v21
	v_pk_add_f32 v[14:15], v[14:15], v[70:71]
	v_pk_add_f32 v[10:11], v[10:11], v[66:67]
	v_pk_mul_f32 v[14:15], v[14:15], s[88:89] op_sel_hi:[1,0]
	v_pk_add_f32 v[20:21], v[20:21], 1.0 op_sel_hi:[1,0]
	v_exp_f32_e32 v14, v14
	v_rcp_f32_e32 v20, v20
	v_rcp_f32_e32 v21, v21
	v_exp_f32_e32 v15, v15
	v_pk_mul_f32 v[10:11], v[10:11], s[88:89] op_sel_hi:[1,0]
	v_pk_add_f32 v[16:17], v[16:17], v[72:73]
	v_exp_f32_e32 v10, v10
	v_pk_add_f32 v[14:15], v[14:15], 1.0 op_sel_hi:[1,0]
	v_exp_f32_e32 v11, v11
	v_rcp_f32_e32 v14, v14
	v_rcp_f32_e32 v15, v15
	v_pk_add_f32 v[12:13], v[12:13], v[68:69]
	v_pk_add_f32 v[10:11], v[10:11], 1.0 op_sel_hi:[1,0]
	v_pk_mul_f32 v[12:13], v[12:13], s[88:89] op_sel_hi:[1,0]
	s_waitcnt lgkmcnt(0)
	v_lshlrev_b32_e32 v74, 16, v224
	v_and_b32_e32 v75, 0xffff0000, v224
	v_pk_mul_f32 v[50:51], v[50:51], v[74:75]
	v_lshlrev_b32_e32 v64, 16, v225
	v_cvt_f16_f32_sdwa v50, v50 dst_sel:WORD_1 dst_unused:UNUSED_PAD src0_sel:DWORD
	v_cvt_f16_f32_sdwa v51, v51 dst_sel:WORD_1 dst_unused:UNUSED_PAD src0_sel:DWORD
	v_and_b32_e32 v65, 0xffff0000, v225
	v_pk_mul_f32 v[14:15], v[14:15], v[58:59]
	v_or_b32_e32 v50, v50, v54
	v_cvt_f16_f32_e32 v54, v55
	v_rcp_f32_e32 v10, v10
	v_rcp_f32_e32 v11, v11
	v_exp_f32_e32 v12, v12
	v_or_b32_e32 v51, v51, v54
	v_pk_mul_f32 v[54:55], v[56:57], s[88:89] op_sel_hi:[1,0]
	v_exp_f32_e32 v13, v13
	v_exp_f32_e32 v54, v54
	v_exp_f32_e32 v55, v55
	v_pk_add_f32 v[6:7], v[6:7], v[70:71]
	v_pk_add_f32 v[12:13], v[12:13], 1.0 op_sel_hi:[1,0]
	v_pk_mul_f32 v[6:7], v[6:7], s[88:89] op_sel_hi:[1,0]
	v_pk_add_f32 v[54:55], v[54:55], 1.0 op_sel_hi:[1,0]
	v_rcp_f32_e32 v12, v12
	v_rcp_f32_e32 v54, v54
	v_rcp_f32_e32 v55, v55
	v_rcp_f32_e32 v13, v13
	v_exp_f32_e32 v6, v6
	v_exp_f32_e32 v7, v7
	v_pk_mul_f32 v[54:55], v[54:55], v[60:61]
	v_pk_add_f32 v[2:3], v[2:3], v[66:67]
	v_pk_mul_f32 v[56:57], v[54:55], s[82:83] op_sel_hi:[1,0]
	v_cvt_f16_f32_e32 v54, v54
	v_exp_f32_e32 v56, v56
	v_exp_f32_e32 v57, v57
	v_pk_add_f32 v[6:7], v[6:7], 1.0 op_sel_hi:[1,0]
	v_pk_mul_f32 v[2:3], v[2:3], s[88:89] op_sel_hi:[1,0]
	v_rcp_f32_e32 v6, v6
	v_pk_add_f32 v[56:57], v[56:57], 1.0 op_sel_hi:[1,0] neg_lo:[1,0] neg_hi:[1,0]
	v_rcp_f32_e32 v7, v7
	v_max_f32_e32 v57, 0, v57
	v_max_f32_e32 v56, 0, v56
	v_sqrt_f32_e32 v56, v56
	v_sqrt_f32_e32 v57, v57
	v_pk_mul_f32 v[6:7], v[6:7], v[58:59]
	v_exp_f32_e32 v2, v2
	v_exp_f32_e32 v3, v3
	v_pk_mul_f32 v[52:53], v[52:53], v[56:57]
	v_pk_mul_f32 v[56:57], v[46:47], s[82:83] op_sel_hi:[1,0]
	v_pk_mul_f32 v[52:53], v[52:53], v[64:65]
	v_exp_f32_e32 v56, v56
	v_cvt_f16_f32_sdwa v52, v52 dst_sel:WORD_1 dst_unused:UNUSED_PAD src0_sel:DWORD
	v_cvt_f16_f32_sdwa v53, v53 dst_sel:WORD_1 dst_unused:UNUSED_PAD src0_sel:DWORD
	v_exp_f32_e32 v57, v57
	v_cvt_f16_f32_e32 v46, v46
	v_or_b32_e32 v52, v52, v54
	v_cvt_f16_f32_e32 v54, v55
	v_pk_add_f32 v[56:57], v[56:57], 1.0 op_sel_hi:[1,0] neg_lo:[1,0] neg_hi:[1,0]
	v_pk_add_f32 v[2:3], v[2:3], 1.0 op_sel_hi:[1,0]
	v_max_f32_e32 v57, 0, v57
	v_or_b32_e32 v53, v53, v54
	v_lshl_add_u64 v[54:55], v[62:63], 2, s[20:21]
	global_store_dwordx4 v[54:55], v[50:53], off
	v_max_f32_e32 v56, 0, v56
	v_sqrt_f32_e32 v56, v56
	v_lshl_add_u64 v[50:51], v[122:123], 0, v[152:153]
	v_sqrt_f32_e32 v57, v57
	v_rcp_f32_e32 v2, v2
	v_rcp_f32_e32 v3, v3
	v_pk_add_f32 v[8:9], v[8:9], v[72:73]
	v_pk_mul_f32 v[42:43], v[42:43], v[56:57]
	v_pk_add_f32 v[4:5], v[4:5], v[68:69]
	s_movk_i32 s0, 0x1000
	v_pk_mul_f32 v[4:5], v[4:5], s[88:89] op_sel_hi:[1,0]
	s_mov_b64 s[6:7], -1
	v_exp_f32_e32 v4, v4
	v_exp_f32_e32 v5, v5
	s_waitcnt lgkmcnt(0)
; __device__ __forceinline__ unsigned pack_f16(float lo, float hi) { const _Float16 a = (_Float16)lo, b = (_Float16)hi; return (unsigned)__builtin_bit_cast(unsigned short, a) | ((unsigned)__builtin_bit_cast(unsigned short, b) << 16); }
;     __device__ __forceinline__ void operator()(const f32x4 (&acc)[2][2][4][2], const Unit& u, int wr, int wc, int fr, int fq) const {
;     ...
;                     for (int j2 = 0; j2 < 2; ++j2) { const int j = 2 * j2;
;                         const f32x2v rp = (f32x2v){acc[ai][0][m][hf][j], acc[ai][0][m][hf][j + 1]} + (f32x2v){bav[j], bav[j + 1]}, ip = (f32x2v){acc[ai][1][m][hf][j], acc[ai][1][m][hf][j + 1]} + (f32x2v){biv[j], biv[j + 1]};
;                         const f32x2v er = rp * (-1.4426950408889634f), ei = ip * (-1.4426950408889634f);
;                         f32x2v tr, ti; tr.x = __builtin_amdgcn_exp2f(er.x); tr.y = __builtin_amdgcn_exp2f(er.y); ti.x = __builtin_amdgcn_exp2f(ei.x); ti.y = __builtin_amdgcn_exp2f(ei.y);
;                         const f32x2v dr = tr + 1.0f, di = ti + 1.0f; f32x2v r, ig; r.x = __builtin_amdgcn_rcpf(dr.x); r.y = __builtin_amdgcn_rcpf(dr.y); ig.x = __builtin_amdgcn_rcpf(di.x); ig.y = __builtin_amdgcn_rcpf(di.y);
;                         const f32x2v la = r * (f32x2v){-sp[j], -sp[j + 1]}, e2 = la * 2.8853900817779268f;
;                         f32x2v a2; a2.x = __builtin_amdgcn_exp2f(e2.x); a2.y = __builtin_amdgcn_exp2f(e2.y);
;                         const f32x2v om = __builtin_elementwise_max(1.0f - a2, (f32x2v){0.f, 0.f}); f32x2v mult; mult.x = __builtin_amdgcn_sqrtf(om.x); mult.y = __builtin_amdgcn_sqrtf(om.y);
;                         const f32x2v bt = (mult * ig) * (f32x2v){xr[j], xr[j + 1]};
;                         w[j] = pack_f16(la.x, bt.x); w[j + 1] = pack_f16(la.y, bt.y); }
;                     *(u32x4*)(AB + off) = w;
	v_lshlrev_b32_e32 v54, 16, v226
	v_and_b32_e32 v55, 0xffff0000, v226
	v_pk_mul_f32 v[42:43], v[42:43], v[54:55]
	v_lshlrev_b32_e32 v52, 16, v227
	v_cvt_f16_f32_sdwa v42, v42 dst_sel:WORD_1 dst_unused:UNUSED_PAD src0_sel:DWORD
	v_cvt_f16_f32_sdwa v43, v43 dst_sel:WORD_1 dst_unused:UNUSED_PAD src0_sel:DWORD
	v_and_b32_e32 v53, 0xffff0000, v227
	v_pk_add_f32 v[4:5], v[4:5], 1.0 op_sel_hi:[1,0]
	v_or_b32_e32 v42, v42, v46
	v_cvt_f16_f32_e32 v46, v47
	v_rcp_f32_e32 v4, v4
	v_rcp_f32_e32 v5, v5
	v_or_b32_e32 v43, v43, v46
	v_pk_mul_f32 v[46:47], v[48:49], s[88:89] op_sel_hi:[1,0]
	s_nop 0
	v_exp_f32_e32 v46, v46
	v_exp_f32_e32 v47, v47
	s_nop 0
	v_pk_add_f32 v[46:47], v[46:47], 1.0 op_sel_hi:[1,0]
	s_nop 0
	v_rcp_f32_e32 v46, v46
	v_rcp_f32_e32 v47, v47
	s_nop 0
	v_pk_mul_f32 v[46:47], v[46:47], v[60:61]
	s_nop 0
	v_pk_mul_f32 v[48:49], v[46:47], s[82:83] op_sel_hi:[1,0]
	v_cvt_f16_f32_e32 v46, v46
	v_exp_f32_e32 v48, v48
	v_exp_f32_e32 v49, v49
	s_nop 0
	v_pk_add_f32 v[48:49], v[48:49], 1.0 op_sel_hi:[1,0] neg_lo:[1,0] neg_hi:[1,0]
	s_nop 0
	v_max_f32_e32 v49, 0, v49
	v_max_f32_e32 v48, 0, v48
	v_sqrt_f32_e32 v48, v48
	v_sqrt_f32_e32 v49, v49
	s_nop 0
	v_pk_mul_f32 v[44:45], v[44:45], v[48:49]
	s_nop 0
	v_pk_mul_f32 v[44:45], v[44:45], v[52:53]
	v_pk_mul_f32 v[48:49], v[38:39], s[82:83] op_sel_hi:[1,0]
	v_cvt_f16_f32_sdwa v44, v44 dst_sel:WORD_1 dst_unused:UNUSED_PAD src0_sel:DWORD
	v_cvt_f16_f32_sdwa v45, v45 dst_sel:WORD_1 dst_unused:UNUSED_PAD src0_sel:DWORD
	v_exp_f32_e32 v48, v48
	v_exp_f32_e32 v49, v49
	v_or_b32_e32 v44, v44, v46
	v_cvt_f16_f32_e32 v46, v47
	v_cvt_f16_f32_e32 v38, v38
	v_pk_add_f32 v[48:49], v[48:49], 1.0 op_sel_hi:[1,0] neg_lo:[1,0] neg_hi:[1,0]
	v_or_b32_e32 v45, v45, v46
	v_lshl_add_u64 v[46:47], v[50:51], 2, s[20:21]
	global_store_dwordx4 v[46:47], v[42:45], off
	v_max_f32_e32 v49, 0, v49
	v_max_f32_e32 v48, 0, v48
	v_lshl_add_u64 v[42:43], v[114:115], 0, v[152:153]
	v_sqrt_f32_e32 v48, v48
	v_sqrt_f32_e32 v49, v49
	s_waitcnt lgkmcnt(0)
	v_lshlrev_b32_e32 v46, 16, v228
	v_and_b32_e32 v47, 0xffff0000, v228
	v_pk_mul_f32 v[34:35], v[34:35], v[48:49]
	v_lshlrev_b32_e32 v44, 16, v229
	v_pk_mul_f32 v[34:35], v[34:35], v[46:47]
	v_and_b32_e32 v45, 0xffff0000, v229
	v_cvt_f16_f32_sdwa v34, v34 dst_sel:WORD_1 dst_unused:UNUSED_PAD src0_sel:DWORD
	v_cvt_f16_f32_sdwa v35, v35 dst_sel:WORD_1 dst_unused:UNUSED_PAD src0_sel:DWORD
	v_or_b32_e32 v34, v34, v38
	v_cvt_f16_f32_e32 v38, v39
	v_or_b32_e32 v35, v35, v38
	v_pk_mul_f32 v[38:39], v[40:41], s[88:89] op_sel_hi:[1,0]
	s_nop 0
	v_exp_f32_e32 v38, v38
	v_exp_f32_e32 v39, v39
	s_nop 0
	v_pk_add_f32 v[38:39], v[38:39], 1.0 op_sel_hi:[1,0]
	s_nop 0
	v_rcp_f32_e32 v38, v38
	v_rcp_f32_e32 v39, v39
	s_nop 0
	v_pk_mul_f32 v[38:39], v[38:39], v[60:61]
	s_nop 0
	v_pk_mul_f32 v[40:41], v[38:39], s[82:83] op_sel_hi:[1,0]
	v_cvt_f16_f32_e32 v38, v38
	v_exp_f32_e32 v40, v40
	v_exp_f32_e32 v41, v41
	s_nop 0
	v_pk_add_f32 v[40:41], v[40:41], 1.0 op_sel_hi:[1,0] neg_lo:[1,0] neg_hi:[1,0]
	s_nop 0
	v_max_f32_e32 v41, 0, v41
	v_max_f32_e32 v40, 0, v40
	v_sqrt_f32_e32 v40, v40
	v_sqrt_f32_e32 v41, v41
	s_nop 0
	v_pk_mul_f32 v[36:37], v[36:37], v[40:41]
	s_nop 0
	v_pk_mul_f32 v[36:37], v[36:37], v[44:45]
	v_pk_mul_f32 v[40:41], v[30:31], s[82:83] op_sel_hi:[1,0]
	v_cvt_f16_f32_sdwa v36, v36 dst_sel:WORD_1 dst_unused:UNUSED_PAD src0_sel:DWORD
	v_cvt_f16_f32_sdwa v37, v37 dst_sel:WORD_1 dst_unused:UNUSED_PAD src0_sel:DWORD
	v_exp_f32_e32 v40, v40
	v_exp_f32_e32 v41, v41
	v_or_b32_e32 v36, v36, v38
	v_cvt_f16_f32_e32 v38, v39
	v_cvt_f16_f32_e32 v30, v30
	v_pk_add_f32 v[40:41], v[40:41], 1.0 op_sel_hi:[1,0] neg_lo:[1,0] neg_hi:[1,0]
	v_or_b32_e32 v37, v37, v38
	v_lshl_add_u64 v[38:39], v[42:43], 2, s[20:21]
	global_store_dwordx4 v[38:39], v[34:37], off
	v_max_f32_e32 v41, 0, v41
	v_max_f32_e32 v40, 0, v40
	v_lshl_add_u64 v[34:35], v[106:107], 0, v[152:153]
	v_sqrt_f32_e32 v40, v40
	v_sqrt_f32_e32 v41, v41
	s_waitcnt lgkmcnt(0)
	v_lshlrev_b32_e32 v38, 16, v230
	v_and_b32_e32 v39, 0xffff0000, v230
	v_pk_mul_f32 v[26:27], v[26:27], v[40:41]
	v_lshlrev_b32_e32 v36, 16, v231
	v_pk_mul_f32 v[26:27], v[26:27], v[38:39]
	v_and_b32_e32 v37, 0xffff0000, v231
	v_cvt_f16_f32_sdwa v26, v26 dst_sel:WORD_1 dst_unused:UNUSED_PAD src0_sel:DWORD
	v_cvt_f16_f32_sdwa v27, v27 dst_sel:WORD_1 dst_unused:UNUSED_PAD src0_sel:DWORD
	v_or_b32_e32 v26, v26, v30
	v_cvt_f16_f32_e32 v30, v31
	v_or_b32_e32 v27, v27, v30
	v_pk_mul_f32 v[30:31], v[32:33], s[88:89] op_sel_hi:[1,0]
	s_nop 0
	v_exp_f32_e32 v30, v30
	v_exp_f32_e32 v31, v31
	s_nop 0
	v_pk_add_f32 v[30:31], v[30:31], 1.0 op_sel_hi:[1,0]
	s_nop 0
	v_rcp_f32_e32 v30, v30
	v_rcp_f32_e32 v31, v31
	s_nop 0
	v_pk_mul_f32 v[30:31], v[30:31], v[60:61]
	s_nop 0
	v_pk_mul_f32 v[32:33], v[30:31], s[82:83] op_sel_hi:[1,0]
	v_cvt_f16_f32_e32 v30, v30
	v_exp_f32_e32 v32, v32
	v_exp_f32_e32 v33, v33
	s_nop 0
	v_pk_add_f32 v[32:33], v[32:33], 1.0 op_sel_hi:[1,0] neg_lo:[1,0] neg_hi:[1,0]
	s_nop 0
	v_max_f32_e32 v33, 0, v33
	v_max_f32_e32 v32, 0, v32
	v_sqrt_f32_e32 v32, v32
	v_sqrt_f32_e32 v33, v33
	s_nop 0
	v_pk_mul_f32 v[28:29], v[28:29], v[32:33]
	s_nop 0
	v_pk_mul_f32 v[28:29], v[28:29], v[36:37]
	v_pk_mul_f32 v[32:33], v[22:23], s[82:83] op_sel_hi:[1,0]
	v_cvt_f16_f32_sdwa v28, v28 dst_sel:WORD_1 dst_unused:UNUSED_PAD src0_sel:DWORD
	v_cvt_f16_f32_sdwa v29, v29 dst_sel:WORD_1 dst_unused:UNUSED_PAD src0_sel:DWORD
	v_exp_f32_e32 v32, v32
	v_exp_f32_e32 v33, v33
	v_or_b32_e32 v28, v28, v30
	v_cvt_f16_f32_e32 v30, v31
	v_cvt_f16_f32_e32 v22, v22
	v_pk_add_f32 v[32:33], v[32:33], 1.0 op_sel_hi:[1,0] neg_lo:[1,0] neg_hi:[1,0]
	v_or_b32_e32 v29, v29, v30
	v_lshl_add_u64 v[30:31], v[34:35], 2, s[20:21]
	global_store_dwordx4 v[30:31], v[26:29], off
	v_max_f32_e32 v33, 0, v33
	v_max_f32_e32 v32, 0, v32
	v_lshl_add_u64 v[26:27], v[98:99], 0, v[152:153]
	v_sqrt_f32_e32 v32, v32
	v_sqrt_f32_e32 v33, v33
	s_waitcnt lgkmcnt(0)
; __device__ __forceinline__ unsigned pack_f16(float lo, float hi) { const _Float16 a = (_Float16)lo, b = (_Float16)hi; return (unsigned)__builtin_bit_cast(unsigned short, a) | ((unsigned)__builtin_bit_cast(unsigned short, b) << 16); }
;     __device__ __forceinline__ void operator()(const f32x4 (&acc)[2][2][4][2], const Unit& u, int wr, int wc, int fr, int fq) const {
;     ...
;                     for (int j2 = 0; j2 < 2; ++j2) { const int j = 2 * j2;
;                         const f32x2v rp = (f32x2v){acc[ai][0][m][hf][j], acc[ai][0][m][hf][j + 1]} + (f32x2v){bav[j], bav[j + 1]}, ip = (f32x2v){acc[ai][1][m][hf][j], acc[ai][1][m][hf][j + 1]} + (f32x2v){biv[j], biv[j + 1]};
;                         const f32x2v er = rp * (-1.4426950408889634f), ei = ip * (-1.4426950408889634f);
;                         f32x2v tr, ti; tr.x = __builtin_amdgcn_exp2f(er.x); tr.y = __builtin_amdgcn_exp2f(er.y); ti.x = __builtin_amdgcn_exp2f(ei.x); ti.y = __builtin_amdgcn_exp2f(ei.y);
;                         const f32x2v dr = tr + 1.0f, di = ti + 1.0f; f32x2v r, ig; r.x = __builtin_amdgcn_rcpf(dr.x); r.y = __builtin_amdgcn_rcpf(dr.y); ig.x = __builtin_amdgcn_rcpf(di.x); ig.y = __builtin_amdgcn_rcpf(di.y);
;                         const f32x2v la = r * (f32x2v){-sp[j], -sp[j + 1]}, e2 = la * 2.8853900817779268f;
;                         f32x2v a2; a2.x = __builtin_amdgcn_exp2f(e2.x); a2.y = __builtin_amdgcn_exp2f(e2.y);
;                         const f32x2v om = __builtin_elementwise_max(1.0f - a2, (f32x2v){0.f, 0.f}); f32x2v mult; mult.x = __builtin_amdgcn_sqrtf(om.x); mult.y = __builtin_amdgcn_sqrtf(om.y);
;                         const f32x2v bt = (mult * ig) * (f32x2v){xr[j], xr[j + 1]};
;                         w[j] = pack_f16(la.x, bt.x); w[j + 1] = pack_f16(la.y, bt.y); }
;                     *(u32x4*)(AB + off) = w;
;     ...
;         asm volatile("s_waitcnt vmcnt(0)" ::: "memory"); __builtin_amdgcn_s_barrier(); asm volatile("" ::: "memory");
	v_lshlrev_b32_e32 v30, 16, v232
	v_and_b32_e32 v31, 0xffff0000, v232
	v_pk_mul_f32 v[18:19], v[18:19], v[32:33]
	v_lshlrev_b32_e32 v28, 16, v233
	v_pk_mul_f32 v[18:19], v[18:19], v[30:31]
	v_and_b32_e32 v29, 0xffff0000, v233
	v_cvt_f16_f32_sdwa v18, v18 dst_sel:WORD_1 dst_unused:UNUSED_PAD src0_sel:DWORD
	v_cvt_f16_f32_sdwa v19, v19 dst_sel:WORD_1 dst_unused:UNUSED_PAD src0_sel:DWORD
	v_or_b32_e32 v18, v18, v22
	v_cvt_f16_f32_e32 v22, v23
	v_or_b32_e32 v19, v19, v22
	v_pk_mul_f32 v[22:23], v[24:25], s[88:89] op_sel_hi:[1,0]
	s_nop 0
	v_exp_f32_e32 v22, v22
	v_exp_f32_e32 v23, v23
	s_nop 0
	v_pk_add_f32 v[22:23], v[22:23], 1.0 op_sel_hi:[1,0]
	s_nop 0
	v_rcp_f32_e32 v22, v22
	v_rcp_f32_e32 v23, v23
	s_nop 0
	v_pk_mul_f32 v[22:23], v[22:23], v[60:61]
	s_nop 0
	v_pk_mul_f32 v[24:25], v[22:23], s[82:83] op_sel_hi:[1,0]
	v_cvt_f16_f32_e32 v22, v22
	v_exp_f32_e32 v24, v24
	v_exp_f32_e32 v25, v25
	s_nop 0
	v_pk_add_f32 v[24:25], v[24:25], 1.0 op_sel_hi:[1,0] neg_lo:[1,0] neg_hi:[1,0]
	s_nop 0
	v_max_f32_e32 v25, 0, v25
	v_max_f32_e32 v24, 0, v24
	v_sqrt_f32_e32 v24, v24
	v_sqrt_f32_e32 v25, v25
	s_nop 0
	v_pk_mul_f32 v[20:21], v[20:21], v[24:25]
	s_nop 0
	v_pk_mul_f32 v[20:21], v[20:21], v[28:29]
	v_pk_mul_f32 v[24:25], v[14:15], s[82:83] op_sel_hi:[1,0]
	v_cvt_f16_f32_sdwa v20, v20 dst_sel:WORD_1 dst_unused:UNUSED_PAD src0_sel:DWORD
	v_cvt_f16_f32_sdwa v21, v21 dst_sel:WORD_1 dst_unused:UNUSED_PAD src0_sel:DWORD
	v_exp_f32_e32 v24, v24
	v_exp_f32_e32 v25, v25
	v_or_b32_e32 v20, v20, v22
	v_cvt_f16_f32_e32 v22, v23
	v_cvt_f16_f32_e32 v14, v14
	v_pk_add_f32 v[24:25], v[24:25], 1.0 op_sel_hi:[1,0] neg_lo:[1,0] neg_hi:[1,0]
	v_or_b32_e32 v21, v21, v22
	v_lshl_add_u64 v[22:23], v[26:27], 2, s[20:21]
	global_store_dwordx4 v[22:23], v[18:21], off
	v_max_f32_e32 v25, 0, v25
	v_max_f32_e32 v24, 0, v24
	v_lshl_add_u64 v[18:19], v[90:91], 0, v[152:153]
	v_sqrt_f32_e32 v24, v24
	v_sqrt_f32_e32 v25, v25
	s_waitcnt lgkmcnt(0)
	v_lshlrev_b32_e32 v22, 16, v234
	v_and_b32_e32 v23, 0xffff0000, v234
	v_pk_mul_f32 v[10:11], v[10:11], v[24:25]
	v_lshlrev_b32_e32 v20, 16, v235
	v_pk_mul_f32 v[10:11], v[10:11], v[22:23]
	v_and_b32_e32 v21, 0xffff0000, v235
	v_cvt_f16_f32_sdwa v10, v10 dst_sel:WORD_1 dst_unused:UNUSED_PAD src0_sel:DWORD
	v_cvt_f16_f32_sdwa v11, v11 dst_sel:WORD_1 dst_unused:UNUSED_PAD src0_sel:DWORD
	v_or_b32_e32 v10, v10, v14
	v_cvt_f16_f32_e32 v14, v15
	v_or_b32_e32 v11, v11, v14
	v_pk_mul_f32 v[14:15], v[16:17], s[88:89] op_sel_hi:[1,0]
	s_nop 0
	v_exp_f32_e32 v14, v14
	v_exp_f32_e32 v15, v15
	s_nop 0
	v_pk_add_f32 v[14:15], v[14:15], 1.0 op_sel_hi:[1,0]
	s_nop 0
	v_rcp_f32_e32 v14, v14
	v_rcp_f32_e32 v15, v15
	s_nop 0
	v_pk_mul_f32 v[14:15], v[14:15], v[60:61]
	s_nop 0
	v_pk_mul_f32 v[16:17], v[14:15], s[82:83] op_sel_hi:[1,0]
	v_cvt_f16_f32_e32 v14, v14
	v_exp_f32_e32 v16, v16
	v_exp_f32_e32 v17, v17
	s_nop 0
	v_pk_add_f32 v[16:17], v[16:17], 1.0 op_sel_hi:[1,0] neg_lo:[1,0] neg_hi:[1,0]
	s_nop 0
	v_max_f32_e32 v17, 0, v17
	v_max_f32_e32 v16, 0, v16
	v_sqrt_f32_e32 v16, v16
	v_sqrt_f32_e32 v17, v17
	s_nop 0
	v_pk_mul_f32 v[12:13], v[12:13], v[16:17]
	s_nop 0
	v_pk_mul_f32 v[12:13], v[12:13], v[20:21]
	v_pk_mul_f32 v[16:17], v[6:7], s[82:83] op_sel_hi:[1,0]
	v_cvt_f16_f32_sdwa v12, v12 dst_sel:WORD_1 dst_unused:UNUSED_PAD src0_sel:DWORD
	v_cvt_f16_f32_sdwa v13, v13 dst_sel:WORD_1 dst_unused:UNUSED_PAD src0_sel:DWORD
	v_exp_f32_e32 v16, v16
	v_exp_f32_e32 v17, v17
	v_or_b32_e32 v12, v12, v14
	v_cvt_f16_f32_e32 v14, v15
	v_cvt_f16_f32_e32 v6, v6
	v_pk_add_f32 v[16:17], v[16:17], 1.0 op_sel_hi:[1,0] neg_lo:[1,0] neg_hi:[1,0]
	v_or_b32_e32 v13, v13, v14
	v_lshl_add_u64 v[14:15], v[18:19], 2, s[20:21]
	global_store_dwordx4 v[14:15], v[10:13], off
	v_max_f32_e32 v17, 0, v17
	v_max_f32_e32 v16, 0, v16
	v_lshl_add_u64 v[10:11], v[78:79], 0, v[152:153]
	v_sqrt_f32_e32 v16, v16
	v_sqrt_f32_e32 v17, v17
	s_waitcnt lgkmcnt(0)
	v_lshlrev_b32_e32 v14, 16, v236
	v_and_b32_e32 v15, 0xffff0000, v236
	v_pk_mul_f32 v[2:3], v[2:3], v[16:17]
	v_lshlrev_b32_e32 v12, 16, v237
	v_pk_mul_f32 v[2:3], v[2:3], v[14:15]
	v_and_b32_e32 v13, 0xffff0000, v237
	v_cvt_f16_f32_sdwa v2, v2 dst_sel:WORD_1 dst_unused:UNUSED_PAD src0_sel:DWORD
	v_cvt_f16_f32_sdwa v3, v3 dst_sel:WORD_1 dst_unused:UNUSED_PAD src0_sel:DWORD
	v_or_b32_e32 v2, v2, v6
	v_cvt_f16_f32_e32 v6, v7
	v_or_b32_e32 v3, v3, v6
	v_pk_mul_f32 v[6:7], v[8:9], s[88:89] op_sel_hi:[1,0]
	s_nop 0
	v_exp_f32_e32 v6, v6
	v_exp_f32_e32 v7, v7
	s_nop 0
	v_pk_add_f32 v[6:7], v[6:7], 1.0 op_sel_hi:[1,0]
	s_nop 0
	v_rcp_f32_e32 v6, v6
	v_rcp_f32_e32 v7, v7
	s_nop 0
	v_pk_mul_f32 v[6:7], v[6:7], v[60:61]
	s_nop 0
	v_pk_mul_f32 v[8:9], v[6:7], s[82:83] op_sel_hi:[1,0]
	v_cvt_f16_f32_e32 v6, v6
	v_exp_f32_e32 v8, v8
	v_exp_f32_e32 v9, v9
	s_nop 0
	v_pk_add_f32 v[8:9], v[8:9], 1.0 op_sel_hi:[1,0] neg_lo:[1,0] neg_hi:[1,0]
	s_nop 0
	v_max_f32_e32 v9, 0, v9
	v_max_f32_e32 v8, 0, v8
	v_sqrt_f32_e32 v8, v8
	v_sqrt_f32_e32 v9, v9
	s_nop 0
	v_pk_mul_f32 v[4:5], v[4:5], v[8:9]
	s_nop 0
	v_pk_mul_f32 v[4:5], v[4:5], v[12:13]
	s_nop 0
	v_cvt_f16_f32_sdwa v4, v4 dst_sel:WORD_1 dst_unused:UNUSED_PAD src0_sel:DWORD
	v_cvt_f16_f32_sdwa v5, v5 dst_sel:WORD_1 dst_unused:UNUSED_PAD src0_sel:DWORD
	v_or_b32_e32 v4, v4, v6
	v_cvt_f16_f32_e32 v6, v7
	v_or_b32_e32 v5, v5, v6
	v_lshl_add_u64 v[6:7], v[10:11], 2, s[20:21]
	global_store_dwordx4 v[6:7], v[2:5], off
	s_waitcnt vmcnt(0)
	s_barrier
; __device__ __forceinline__ float f16_lo(unsigned w) { return (float)__builtin_bit_cast(_Float16, (unsigned short)(w & 0xffffu)); }
; __device__ __forceinline__ float f16_hi(unsigned w) { return (float)__builtin_bit_cast(_Float16, (unsigned short)(w >> 16)); }
;     __device__ __forceinline__ void operator()(const f32x4 (&acc)[2][2][4][2], const Unit& u, int wr, int wc, int fr, int fq) const {
;     ...
;         { const int t = (4 * wr + wc) * 64 + fq * 16 + fr, chunk = t >> 7, c = (u.pn >> 1) * 256 + (u.pn & 1) * 128 + (t & 127), r0 = u.pm * BM + chunk * 64;
;           const unsigned* ab = AB + (size_t)r0 * D + c; float h = 0.f, L = 0.f;
; #pragma unroll
;           for (int b4 = 0; b4 < 4; ++b4) { unsigned w[16];
; #pragma unroll
;               for (int i = 0; i < 16; ++i) w[i] = ab[(size_t)(b4 * 16 + i) * D];
; #pragma unroll
;               for (int i = 0; i < 16; ++i) { const float la = f16_lo(w[i]); h = __expf(la) * h + f16_hi(w[i]); L += la; } }
	s_nop 0
	v_and_b32_e32 v2, -16, v170
	v_add_u32_e32 v3, s54, v2
	v_and_b32_e32 v2, 0x70, v3
	v_ashrrev_i32_e32 v3, 1, v3
	v_and_b32_e32 v3, 0xffffffc0, v3
	v_add_u32_e32 v4, s39, v3
	v_ashrrev_i32_e32 v5, 31, v4
	v_or3_b32 v2, s38, v2, v171
	v_lshlrev_b64 v[6:7], 12, v[4:5]
	v_lshl_add_u64 v[6:7], s[20:21], 0, v[6:7]
	v_ashrrev_i32_e32 v3, 31, v2
	v_lshl_add_u64 v[6:7], v[2:3], 2, v[6:7]
	global_load_dword v5, v[6:7], off
	v_add_co_u32_e32 v8, vcc, s0, v6
	s_movk_i32 s0, 0x3000
	s_nop 0
	v_addc_co_u32_e32 v9, vcc, 0, v7, vcc
	global_load_dword v10, v[8:9], off
	v_add_co_u32_e32 v8, vcc, s63, v6
	v_ashrrev_i32_e32 v4, 6, v4
	s_nop 0
	v_addc_co_u32_e32 v9, vcc, 0, v7, vcc
	global_load_dword v11, v[8:9], off
	v_add_co_u32_e32 v8, vcc, s0, v6
	s_movk_i32 s0, 0x4000
	s_nop 0
	v_addc_co_u32_e32 v9, vcc, 0, v7, vcc
	global_load_dword v12, v[8:9], off
	v_add_co_u32_e32 v8, vcc, s0, v6
	s_movk_i32 s0, 0x5000
	s_nop 0
	v_addc_co_u32_e32 v9, vcc, 0, v7, vcc
	global_load_dword v13, v[8:9], off
	v_add_co_u32_e32 v8, vcc, s0, v6
	s_movk_i32 s0, 0x6000
	s_nop 0
	v_addc_co_u32_e32 v9, vcc, 0, v7, vcc
	global_load_dword v14, v[8:9], off
	v_add_co_u32_e32 v8, vcc, s0, v6
	s_movk_i32 s0, 0x7000
	s_nop 0
	v_addc_co_u32_e32 v9, vcc, 0, v7, vcc
	global_load_dword v15, v[8:9], off
	v_add_co_u32_e32 v8, vcc, s0, v6
	s_mov_b32 s0, 0x8000
	s_nop 0
	v_addc_co_u32_e32 v9, vcc, 0, v7, vcc
	global_load_dword v16, v[8:9], off
	v_add_co_u32_e32 v8, vcc, s0, v6
	s_mov_b32 s0, 0x9000
	s_nop 0
	v_addc_co_u32_e32 v9, vcc, 0, v7, vcc
	global_load_dword v17, v[8:9], off
	v_add_co_u32_e32 v8, vcc, s0, v6
	s_mov_b32 s0, 0xa000
	s_nop 0
	v_addc_co_u32_e32 v9, vcc, 0, v7, vcc
	global_load_dword v18, v[8:9], off
	v_add_co_u32_e32 v8, vcc, s0, v6
	s_mov_b32 s0, 0xb000
	s_nop 0
	v_addc_co_u32_e32 v9, vcc, 0, v7, vcc
	global_load_dword v19, v[8:9], off
	v_add_co_u32_e32 v8, vcc, s0, v6
	s_mov_b32 s0, 0xc000
	s_nop 0
	v_addc_co_u32_e32 v9, vcc, 0, v7, vcc
	global_load_dword v20, v[8:9], off
	v_add_co_u32_e32 v8, vcc, s0, v6
	s_mov_b32 s0, 0xd000
	s_nop 0
	v_addc_co_u32_e32 v9, vcc, 0, v7, vcc
	global_load_dword v21, v[8:9], off
	v_add_co_u32_e32 v8, vcc, s0, v6
	s_mov_b32 s0, 0xe000
	s_nop 0
	v_addc_co_u32_e32 v9, vcc, 0, v7, vcc
	global_load_dword v22, v[8:9], off
	v_add_co_u32_e32 v8, vcc, s0, v6
	s_mov_b32 s0, 0xf000
	s_nop 0
	v_addc_co_u32_e32 v9, vcc, 0, v7, vcc
	global_load_dword v23, v[8:9], off
	v_add_co_u32_e32 v8, vcc, s0, v6
	s_mov_b32 s0, 0x10000
	s_nop 0
	v_addc_co_u32_e32 v9, vcc, 0, v7, vcc
	global_load_dword v8, v[8:9], off
	s_waitcnt vmcnt(0) lgkmcnt(0)
	v_cvt_f32_f16_e32 v9, v5
	v_mul_f32_e32 v24, 0x3fb8aa3b, v9
	v_exp_f32_e32 v24, v24
	v_add_f32_e32 v9, 0, v9
	v_fma_mix_f32 v5, v24, 0, v5 op_sel:[0,0,1] op_sel_hi:[0,0,1]
	v_cvt_f32_f16_e32 v24, v10
	v_mul_f32_e32 v25, 0x3fb8aa3b, v24
	v_exp_f32_e32 v25, v25
	v_add_f32_e32 v9, v9, v24
	v_fma_mix_f32 v5, v25, v5, v10 op_sel:[0,0,1] op_sel_hi:[0,0,1]
	v_cvt_f32_f16_e32 v10, v11
	v_mul_f32_e32 v24, 0x3fb8aa3b, v10
	v_exp_f32_e32 v24, v24
	v_add_f32_e32 v9, v9, v10
	v_cvt_f32_f16_e32 v10, v12
	v_fma_mix_f32 v5, v24, v5, v11 op_sel:[0,0,1] op_sel_hi:[0,0,1]
	v_mul_f32_e32 v11, 0x3fb8aa3b, v10
	v_exp_f32_e32 v11, v11
	v_add_f32_e32 v9, v9, v10
	v_cvt_f32_f16_e32 v10, v13
	v_fma_mix_f32 v5, v11, v5, v12 op_sel:[0,0,1] op_sel_hi:[0,0,1]
	v_mul_f32_e32 v11, 0x3fb8aa3b, v10
	v_exp_f32_e32 v11, v11
	v_add_f32_e32 v9, v9, v10
	v_cvt_f32_f16_e32 v10, v14
	v_fma_mix_f32 v5, v11, v5, v13 op_sel:[0,0,1] op_sel_hi:[0,0,1]
	v_mul_f32_e32 v11, 0x3fb8aa3b, v10
	v_exp_f32_e32 v11, v11
	v_add_f32_e32 v9, v9, v10
	v_cvt_f32_f16_e32 v10, v15
	v_fma_mix_f32 v5, v11, v5, v14 op_sel:[0,0,1] op_sel_hi:[0,0,1]
	v_mul_f32_e32 v11, 0x3fb8aa3b, v10
	v_exp_f32_e32 v11, v11
	v_add_f32_e32 v9, v9, v10
	v_cvt_f32_f16_e32 v10, v16
	v_fma_mix_f32 v5, v11, v5, v15 op_sel:[0,0,1] op_sel_hi:[0,0,1]
	v_mul_f32_e32 v11, 0x3fb8aa3b, v10
	v_exp_f32_e32 v11, v11
	v_add_f32_e32 v9, v9, v10
	v_cvt_f32_f16_e32 v10, v17
	v_fma_mix_f32 v5, v11, v5, v16 op_sel:[0,0,1] op_sel_hi:[0,0,1]
	v_mul_f32_e32 v11, 0x3fb8aa3b, v10
	v_exp_f32_e32 v11, v11
	v_add_f32_e32 v9, v9, v10
	v_cvt_f32_f16_e32 v10, v18
	v_fma_mix_f32 v5, v11, v5, v17 op_sel:[0,0,1] op_sel_hi:[0,0,1]
	v_mul_f32_e32 v11, 0x3fb8aa3b, v10
	v_exp_f32_e32 v11, v11
	v_add_f32_e32 v9, v9, v10
	v_cvt_f32_f16_e32 v10, v19
	v_fma_mix_f32 v5, v11, v5, v18 op_sel:[0,0,1] op_sel_hi:[0,0,1]
	v_mul_f32_e32 v11, 0x3fb8aa3b, v10
	v_exp_f32_e32 v11, v11
	v_add_f32_e32 v9, v9, v10
	v_cvt_f32_f16_e32 v10, v20
	v_fma_mix_f32 v5, v11, v5, v19 op_sel:[0,0,1] op_sel_hi:[0,0,1]
	v_mul_f32_e32 v11, 0x3fb8aa3b, v10
	v_exp_f32_e32 v11, v11
	v_add_f32_e32 v9, v9, v10
	v_cvt_f32_f16_e32 v10, v21
	v_fma_mix_f32 v5, v11, v5, v20 op_sel:[0,0,1] op_sel_hi:[0,0,1]
	v_mul_f32_e32 v11, 0x3fb8aa3b, v10
	v_exp_f32_e32 v11, v11
	v_add_f32_e32 v9, v9, v10
	v_cvt_f32_f16_e32 v10, v22
	v_fma_mix_f32 v5, v11, v5, v21 op_sel:[0,0,1] op_sel_hi:[0,0,1]
	v_mul_f32_e32 v11, 0x3fb8aa3b, v10
	v_exp_f32_e32 v11, v11
	v_add_f32_e32 v9, v9, v10
	v_cvt_f32_f16_e32 v10, v23
	v_fma_mix_f32 v5, v11, v5, v22 op_sel:[0,0,1] op_sel_hi:[0,0,1]
	v_mul_f32_e32 v11, 0x3fb8aa3b, v10
	v_exp_f32_e32 v11, v11
	v_add_f32_e32 v9, v9, v10
	v_cvt_f32_f16_e32 v10, v8
	v_fma_mix_f32 v5, v11, v5, v23 op_sel:[0,0,1] op_sel_hi:[0,0,1]
	v_mul_f32_e32 v11, 0x3fb8aa3b, v10
	v_exp_f32_e32 v11, v11
	v_add_f32_e32 v15, v9, v10
	v_fma_mix_f32 v14, v11, v5, v8 op_sel:[0,0,1] op_sel_hi:[0,0,1]
	v_add_co_u32_e32 v8, vcc, s0, v6
	s_mov_b32 s0, 0x11000
	s_nop 0
	v_addc_co_u32_e32 v9, vcc, 0, v7, vcc
	global_load_dword v16, v[8:9], off
	v_add_co_u32_e32 v8, vcc, s0, v6
	s_mov_b32 s0, 0x12000
; __device__ __forceinline__ float f16_lo(unsigned w) { return (float)__builtin_bit_cast(_Float16, (unsigned short)(w & 0xffffu)); }
; __device__ __forceinline__ float f16_hi(unsigned w) { return (float)__builtin_bit_cast(_Float16, (unsigned short)(w >> 16)); }
;     __device__ __forceinline__ void operator()(const f32x4 (&acc)[2][2][4][2], const Unit& u, int wr, int wc, int fr, int fq) const {
;     ...
;           for (int b4 = 0; b4 < 4; ++b4) { unsigned w[16];
; #pragma unroll
;               for (int i = 0; i < 16; ++i) w[i] = ab[(size_t)(b4 * 16 + i) * D];
; #pragma unroll
;               for (int i = 0; i < 16; ++i) { const float la = f16_lo(w[i]); h = __expf(la) * h + f16_hi(w[i]); L += la; } }
	s_nop 0
	v_addc_co_u32_e32 v9, vcc, 0, v7, vcc
	global_load_dword v13, v[8:9], off
	v_add_co_u32_e32 v8, vcc, s0, v6
	s_mov_b32 s0, 0x13000
	s_nop 0
	v_addc_co_u32_e32 v9, vcc, 0, v7, vcc
	global_load_dword v12, v[8:9], off
	v_add_co_u32_e32 v8, vcc, s0, v6
	s_mov_b32 s0, 0x14000
	s_nop 0
	v_addc_co_u32_e32 v9, vcc, 0, v7, vcc
	global_load_dword v11, v[8:9], off
	v_add_co_u32_e32 v8, vcc, s0, v6
	s_mov_b32 s0, 0x15000
	s_nop 0
	v_addc_co_u32_e32 v9, vcc, 0, v7, vcc
	global_load_dword v10, v[8:9], off
	v_add_co_u32_e32 v8, vcc, s0, v6
	s_mov_b32 s0, 0x16000
	s_nop 0
	v_addc_co_u32_e32 v9, vcc, 0, v7, vcc
	global_load_dword v9, v[8:9], off
	v_add_co_u32_e32 v18, vcc, s0, v6
	s_mov_b32 s0, 0x17000
	s_nop 0
	v_addc_co_u32_e32 v19, vcc, 0, v7, vcc
	global_load_dword v8, v[18:19], off
	v_add_co_u32_e32 v18, vcc, s0, v6
	s_mov_b32 s0, 0x18000
	s_nop 0
	v_addc_co_u32_e32 v19, vcc, 0, v7, vcc
	global_load_dword v5, v[18:19], off
	v_add_co_u32_e32 v18, vcc, s0, v6
	s_mov_b32 s0, 0x19000
	s_nop 0
	v_addc_co_u32_e32 v19, vcc, 0, v7, vcc
	global_load_dword v22, v[18:19], off
	v_add_co_u32_e32 v18, vcc, s0, v6
	s_mov_b32 s0, 0x1a000
	s_nop 0
	v_addc_co_u32_e32 v19, vcc, 0, v7, vcc
	global_load_dword v21, v[18:19], off
	v_add_co_u32_e32 v18, vcc, s0, v6
	s_mov_b32 s0, 0x1b000
	s_nop 0
	v_addc_co_u32_e32 v19, vcc, 0, v7, vcc
	global_load_dword v20, v[18:19], off
	v_add_co_u32_e32 v18, vcc, s0, v6
	s_mov_b32 s0, 0x1c000
	s_nop 0
	v_addc_co_u32_e32 v19, vcc, 0, v7, vcc
	v_add_co_u32_e32 v24, vcc, s0, v6
	s_mov_b32 s0, 0x1d000
	s_nop 0
	v_addc_co_u32_e32 v25, vcc, 0, v7, vcc
	global_load_dword v19, v[18:19], off
	s_nop 0
	global_load_dword v18, v[24:25], off
	v_add_co_u32_e32 v24, vcc, s0, v6
	s_mov_b32 s0, 0x1e000
	s_nop 0
	v_addc_co_u32_e32 v25, vcc, 0, v7, vcc
	global_load_dword v17, v[24:25], off
	v_add_co_u32_e32 v24, vcc, s0, v6
	s_mov_b32 s0, 0x1f000
	s_nop 0
	v_addc_co_u32_e32 v25, vcc, 0, v7, vcc
	global_load_dword v23, v[24:25], off
	v_add_co_u32_e32 v24, vcc, s0, v6
	s_mov_b32 s0, 0x20000
	s_nop 0
	v_addc_co_u32_e32 v25, vcc, 0, v7, vcc
	global_load_dword v24, v[24:25], off
	s_waitcnt vmcnt(0) lgkmcnt(0)
	v_cvt_f32_f16_e32 v25, v16
	v_mul_f32_e32 v26, 0x3fb8aa3b, v25
	v_exp_f32_e32 v26, v26
	v_add_f32_e32 v15, v15, v25
	v_fma_mix_f32 v14, v26, v14, v16 op_sel:[0,0,1] op_sel_hi:[0,0,1]
	v_cvt_f32_f16_e32 v16, v13
	v_mul_f32_e32 v25, 0x3fb8aa3b, v16
	v_exp_f32_e32 v25, v25
	s_nop 0
	v_fma_mix_f32 v13, v25, v14, v13 op_sel:[0,0,1] op_sel_hi:[0,0,1]
	v_add_f32_e32 v14, v15, v16
	v_cvt_f32_f16_e32 v15, v12
	v_mul_f32_e32 v16, 0x3fb8aa3b, v15
	v_exp_f32_e32 v16, v16
	s_nop 0
	v_fma_mix_f32 v12, v16, v13, v12 op_sel:[0,0,1] op_sel_hi:[0,0,1]
	v_add_f32_e32 v13, v14, v15
	v_cvt_f32_f16_e32 v14, v11
	v_mul_f32_e32 v15, 0x3fb8aa3b, v14
	v_exp_f32_e32 v15, v15
	s_nop 0
	v_fma_mix_f32 v11, v15, v12, v11 op_sel:[0,0,1] op_sel_hi:[0,0,1]
	v_add_f32_e32 v12, v13, v14
	v_cvt_f32_f16_e32 v13, v10
	v_mul_f32_e32 v14, 0x3fb8aa3b, v13
	v_exp_f32_e32 v14, v14
	s_nop 0
	v_fma_mix_f32 v10, v14, v11, v10 op_sel:[0,0,1] op_sel_hi:[0,0,1]
	v_add_f32_e32 v11, v12, v13
	v_cvt_f32_f16_e32 v12, v9
	v_mul_f32_e32 v13, 0x3fb8aa3b, v12
	v_exp_f32_e32 v13, v13
	s_nop 0
	v_fma_mix_f32 v9, v13, v10, v9 op_sel:[0,0,1] op_sel_hi:[0,0,1]
	v_add_f32_e32 v10, v11, v12
	v_cvt_f32_f16_e32 v11, v8
	v_mul_f32_e32 v12, 0x3fb8aa3b, v11
	v_exp_f32_e32 v12, v12
	s_nop 0
	v_fma_mix_f32 v8, v12, v9, v8 op_sel:[0,0,1] op_sel_hi:[0,0,1]
	v_add_f32_e32 v9, v10, v11
	v_cvt_f32_f16_e32 v10, v5
	v_mul_f32_e32 v11, 0x3fb8aa3b, v10
	v_exp_f32_e32 v11, v11
	s_nop 0
	v_fma_mix_f32 v5, v11, v8, v5 op_sel:[0,0,1] op_sel_hi:[0,0,1]
	v_add_f32_e32 v8, v9, v10
	v_cvt_f32_f16_e32 v9, v22
	v_mul_f32_e32 v10, 0x3fb8aa3b, v9
	v_exp_f32_e32 v10, v10
	v_add_f32_e32 v8, v8, v9
	v_cvt_f32_f16_e32 v9, v21
	v_fma_mix_f32 v5, v10, v5, v22 op_sel:[0,0,1] op_sel_hi:[0,0,1]
	v_mul_f32_e32 v10, 0x3fb8aa3b, v9
	v_exp_f32_e32 v10, v10
	v_add_f32_e32 v8, v8, v9
	v_cvt_f32_f16_e32 v9, v20
	v_fma_mix_f32 v5, v10, v5, v21 op_sel:[0,0,1] op_sel_hi:[0,0,1]
	v_mul_f32_e32 v10, 0x3fb8aa3b, v9
	v_exp_f32_e32 v10, v10
	v_add_f32_e32 v8, v8, v9
	v_cvt_f32_f16_e32 v9, v19
	v_fma_mix_f32 v5, v10, v5, v20 op_sel:[0,0,1] op_sel_hi:[0,0,1]
	v_mul_f32_e32 v10, 0x3fb8aa3b, v9
	v_exp_f32_e32 v10, v10
	v_add_f32_e32 v8, v8, v9
	v_cvt_f32_f16_e32 v9, v18
	v_fma_mix_f32 v5, v10, v5, v19 op_sel:[0,0,1] op_sel_hi:[0,0,1]
	v_mul_f32_e32 v10, 0x3fb8aa3b, v9
	v_exp_f32_e32 v10, v10
	v_add_f32_e32 v8, v8, v9
	v_cvt_f32_f16_e32 v9, v17
	v_fma_mix_f32 v5, v10, v5, v18 op_sel:[0,0,1] op_sel_hi:[0,0,1]
	v_mul_f32_e32 v10, 0x3fb8aa3b, v9
	v_exp_f32_e32 v10, v10
	v_add_f32_e32 v8, v8, v9
	v_cvt_f32_f16_e32 v9, v23
	v_fma_mix_f32 v5, v10, v5, v17 op_sel:[0,0,1] op_sel_hi:[0,0,1]
	v_mul_f32_e32 v10, 0x3fb8aa3b, v9
	v_exp_f32_e32 v10, v10
	v_add_f32_e32 v8, v8, v9
	v_cvt_f32_f16_e32 v9, v24
	v_fma_mix_f32 v5, v10, v5, v23 op_sel:[0,0,1] op_sel_hi:[0,0,1]
	v_mul_f32_e32 v10, 0x3fb8aa3b, v9
	v_exp_f32_e32 v10, v10
	s_nop 0
	v_fma_mix_f32 v5, v10, v5, v24 op_sel:[0,0,1] op_sel_hi:[0,0,1]
	v_add_f32_e32 v10, v8, v9
	v_add_co_u32_e32 v8, vcc, s0, v6
	s_mov_b32 s0, 0x21000
	s_nop 0
	v_addc_co_u32_e32 v9, vcc, 0, v7, vcc
	global_load_dword v11, v[8:9], off
	v_add_co_u32_e32 v8, vcc, s0, v6
	s_mov_b32 s0, 0x22000
	s_nop 0
	v_addc_co_u32_e32 v9, vcc, 0, v7, vcc
	global_load_dword v12, v[8:9], off
	v_add_co_u32_e32 v8, vcc, s0, v6
	s_mov_b32 s0, 0x23000
	s_nop 0
	v_addc_co_u32_e32 v9, vcc, 0, v7, vcc
	global_load_dword v13, v[8:9], off
	v_add_co_u32_e32 v8, vcc, s0, v6
	s_mov_b32 s0, 0x24000
	s_nop 0
	v_addc_co_u32_e32 v9, vcc, 0, v7, vcc
	global_load_dword v14, v[8:9], off
; __device__ __forceinline__ float f16_lo(unsigned w) { return (float)__builtin_bit_cast(_Float16, (unsigned short)(w & 0xffffu)); }
; __device__ __forceinline__ float f16_hi(unsigned w) { return (float)__builtin_bit_cast(_Float16, (unsigned short)(w >> 16)); }
;     __device__ __forceinline__ void operator()(const f32x4 (&acc)[2][2][4][2], const Unit& u, int wr, int wc, int fr, int fq) const {
;     ...
;           for (int b4 = 0; b4 < 4; ++b4) { unsigned w[16];
; #pragma unroll
;               for (int i = 0; i < 16; ++i) w[i] = ab[(size_t)(b4 * 16 + i) * D];
; #pragma unroll
;               for (int i = 0; i < 16; ++i) { const float la = f16_lo(w[i]); h = __expf(la) * h + f16_hi(w[i]); L += la; } }
	v_add_co_u32_e32 v8, vcc, s0, v6
	s_mov_b32 s0, 0x25000
	s_nop 0
	v_addc_co_u32_e32 v9, vcc, 0, v7, vcc
	global_load_dword v15, v[8:9], off
	v_add_co_u32_e32 v8, vcc, s0, v6
	s_mov_b32 s0, 0x26000
	s_nop 0
	v_addc_co_u32_e32 v9, vcc, 0, v7, vcc
	global_load_dword v16, v[8:9], off
	v_add_co_u32_e32 v8, vcc, s0, v6
	s_mov_b32 s0, 0x27000
	s_nop 0
	v_addc_co_u32_e32 v9, vcc, 0, v7, vcc
	global_load_dword v17, v[8:9], off
	v_add_co_u32_e32 v8, vcc, s0, v6
	s_mov_b32 s0, 0x28000
	s_nop 0
	v_addc_co_u32_e32 v9, vcc, 0, v7, vcc
	global_load_dword v18, v[8:9], off
	v_add_co_u32_e32 v8, vcc, s0, v6
	s_mov_b32 s0, 0x29000
	s_nop 0
	v_addc_co_u32_e32 v9, vcc, 0, v7, vcc
	global_load_dword v19, v[8:9], off
	v_add_co_u32_e32 v8, vcc, s0, v6
	s_mov_b32 s0, 0x2a000
	s_nop 0
	v_addc_co_u32_e32 v9, vcc, 0, v7, vcc
	global_load_dword v20, v[8:9], off
	v_add_co_u32_e32 v8, vcc, s0, v6
	s_mov_b32 s0, 0x2b000
	s_nop 0
	v_addc_co_u32_e32 v9, vcc, 0, v7, vcc
	global_load_dword v21, v[8:9], off
	v_add_co_u32_e32 v8, vcc, s0, v6
	s_mov_b32 s0, 0x2c000
	s_nop 0
	v_addc_co_u32_e32 v9, vcc, 0, v7, vcc
	global_load_dword v22, v[8:9], off
	v_add_co_u32_e32 v8, vcc, s0, v6
	s_mov_b32 s0, 0x2d000
	s_nop 0
	v_addc_co_u32_e32 v9, vcc, 0, v7, vcc
	global_load_dword v23, v[8:9], off
	v_add_co_u32_e32 v8, vcc, s0, v6
	s_mov_b32 s0, 0x2e000
	s_nop 0
	v_addc_co_u32_e32 v9, vcc, 0, v7, vcc
	global_load_dword v24, v[8:9], off
	v_add_co_u32_e32 v8, vcc, s0, v6
	s_mov_b32 s0, 0x2f000
	s_nop 0
	v_addc_co_u32_e32 v9, vcc, 0, v7, vcc
	global_load_dword v25, v[8:9], off
	v_add_co_u32_e32 v8, vcc, s0, v6
	s_mov_b32 s0, 0x30000
	s_nop 0
	v_addc_co_u32_e32 v9, vcc, 0, v7, vcc
	global_load_dword v8, v[8:9], off
	s_waitcnt vmcnt(0) lgkmcnt(0)
	v_cvt_f32_f16_e32 v9, v11
	v_mul_f32_e32 v26, 0x3fb8aa3b, v9
	v_exp_f32_e32 v26, v26
	v_add_f32_e32 v9, v10, v9
	v_cvt_f32_f16_e32 v10, v12
	v_fma_mix_f32 v5, v26, v5, v11 op_sel:[0,0,1] op_sel_hi:[0,0,1]
	v_mul_f32_e32 v11, 0x3fb8aa3b, v10
	v_exp_f32_e32 v11, v11
	v_add_f32_e32 v9, v9, v10
	v_cvt_f32_f16_e32 v10, v13
	v_fma_mix_f32 v5, v11, v5, v12 op_sel:[0,0,1] op_sel_hi:[0,0,1]
	v_mul_f32_e32 v11, 0x3fb8aa3b, v10
	v_exp_f32_e32 v11, v11
	v_add_f32_e32 v9, v9, v10
	v_cvt_f32_f16_e32 v10, v14
	v_fma_mix_f32 v5, v11, v5, v13 op_sel:[0,0,1] op_sel_hi:[0,0,1]
	v_mul_f32_e32 v11, 0x3fb8aa3b, v10
	v_exp_f32_e32 v11, v11
	v_add_f32_e32 v9, v9, v10
	v_cvt_f32_f16_e32 v10, v15
	v_fma_mix_f32 v5, v11, v5, v14 op_sel:[0,0,1] op_sel_hi:[0,0,1]
	v_mul_f32_e32 v11, 0x3fb8aa3b, v10
	v_exp_f32_e32 v11, v11
	v_add_f32_e32 v9, v9, v10
	v_cvt_f32_f16_e32 v10, v16
	v_fma_mix_f32 v5, v11, v5, v15 op_sel:[0,0,1] op_sel_hi:[0,0,1]
	v_mul_f32_e32 v11, 0x3fb8aa3b, v10
	v_exp_f32_e32 v11, v11
	v_add_f32_e32 v9, v9, v10
	v_cvt_f32_f16_e32 v10, v17
	v_fma_mix_f32 v5, v11, v5, v16 op_sel:[0,0,1] op_sel_hi:[0,0,1]
	v_mul_f32_e32 v11, 0x3fb8aa3b, v10
	v_exp_f32_e32 v11, v11
	v_add_f32_e32 v9, v9, v10
	v_cvt_f32_f16_e32 v10, v18
	v_fma_mix_f32 v5, v11, v5, v17 op_sel:[0,0,1] op_sel_hi:[0,0,1]
	v_mul_f32_e32 v11, 0x3fb8aa3b, v10
	v_exp_f32_e32 v11, v11
	v_add_f32_e32 v9, v9, v10
	v_cvt_f32_f16_e32 v10, v19
	v_fma_mix_f32 v5, v11, v5, v18 op_sel:[0,0,1] op_sel_hi:[0,0,1]
	v_mul_f32_e32 v11, 0x3fb8aa3b, v10
	v_exp_f32_e32 v11, v11
	v_add_f32_e32 v9, v9, v10
	v_cvt_f32_f16_e32 v10, v20
	v_fma_mix_f32 v5, v11, v5, v19 op_sel:[0,0,1] op_sel_hi:[0,0,1]
	v_mul_f32_e32 v11, 0x3fb8aa3b, v10
	v_exp_f32_e32 v11, v11
	v_add_f32_e32 v9, v9, v10
	v_cvt_f32_f16_e32 v10, v21
	v_fma_mix_f32 v5, v11, v5, v20 op_sel:[0,0,1] op_sel_hi:[0,0,1]
	v_mul_f32_e32 v11, 0x3fb8aa3b, v10
	v_exp_f32_e32 v11, v11
	v_add_f32_e32 v9, v9, v10
	v_cvt_f32_f16_e32 v10, v22
	v_fma_mix_f32 v5, v11, v5, v21 op_sel:[0,0,1] op_sel_hi:[0,0,1]
	v_mul_f32_e32 v11, 0x3fb8aa3b, v10
	v_exp_f32_e32 v11, v11
	v_add_f32_e32 v9, v9, v10
	v_cvt_f32_f16_e32 v10, v23
	v_fma_mix_f32 v5, v11, v5, v22 op_sel:[0,0,1] op_sel_hi:[0,0,1]
	v_mul_f32_e32 v11, 0x3fb8aa3b, v10
	v_exp_f32_e32 v11, v11
	v_add_f32_e32 v9, v9, v10
	v_cvt_f32_f16_e32 v10, v24
	v_fma_mix_f32 v5, v11, v5, v23 op_sel:[0,0,1] op_sel_hi:[0,0,1]
	v_mul_f32_e32 v11, 0x3fb8aa3b, v10
	v_exp_f32_e32 v11, v11
	v_add_f32_e32 v9, v9, v10
	v_cvt_f32_f16_e32 v10, v25
	v_fma_mix_f32 v5, v11, v5, v24 op_sel:[0,0,1] op_sel_hi:[0,0,1]
	v_mul_f32_e32 v11, 0x3fb8aa3b, v10
	v_exp_f32_e32 v11, v11
	v_add_f32_e32 v9, v9, v10
	v_cvt_f32_f16_e32 v10, v8
	v_fma_mix_f32 v5, v11, v5, v25 op_sel:[0,0,1] op_sel_hi:[0,0,1]
	v_mul_f32_e32 v11, 0x3fb8aa3b, v10
	v_exp_f32_e32 v11, v11
	v_add_f32_e32 v10, v9, v10
	v_fma_mix_f32 v5, v11, v5, v8 op_sel:[0,0,1] op_sel_hi:[0,0,1]
	v_add_co_u32_e32 v8, vcc, s0, v6
	s_mov_b32 s0, 0x31000
	s_nop 0
	v_addc_co_u32_e32 v9, vcc, 0, v7, vcc
	global_load_dword v11, v[8:9], off
	v_add_co_u32_e32 v8, vcc, s0, v6
	s_mov_b32 s0, 0x32000
	s_nop 0
	v_addc_co_u32_e32 v9, vcc, 0, v7, vcc
	global_load_dword v12, v[8:9], off
	v_add_co_u32_e32 v8, vcc, s0, v6
	s_mov_b32 s0, 0x33000
	s_nop 0
	v_addc_co_u32_e32 v9, vcc, 0, v7, vcc
	global_load_dword v13, v[8:9], off
	v_add_co_u32_e32 v8, vcc, s0, v6
	s_mov_b32 s0, 0x34000
	s_nop 0
	v_addc_co_u32_e32 v9, vcc, 0, v7, vcc
	global_load_dword v14, v[8:9], off
	v_add_co_u32_e32 v8, vcc, s0, v6
	s_mov_b32 s0, 0x35000
	s_nop 0
	v_addc_co_u32_e32 v9, vcc, 0, v7, vcc
	global_load_dword v15, v[8:9], off
	v_add_co_u32_e32 v8, vcc, s0, v6
	s_mov_b32 s0, 0x36000
	s_nop 0
	v_addc_co_u32_e32 v9, vcc, 0, v7, vcc
	global_load_dword v16, v[8:9], off
	v_add_co_u32_e32 v8, vcc, s0, v6
	s_mov_b32 s0, 0x37000
	s_nop 0
	v_addc_co_u32_e32 v9, vcc, 0, v7, vcc
	global_load_dword v17, v[8:9], off
	v_add_co_u32_e32 v8, vcc, s0, v6
	s_mov_b32 s0, 0x38000
	s_nop 0
	v_addc_co_u32_e32 v9, vcc, 0, v7, vcc
	global_load_dword v18, v[8:9], off
	v_add_co_u32_e32 v8, vcc, s0, v6
	s_mov_b32 s0, 0x39000
	s_nop 0
	v_addc_co_u32_e32 v9, vcc, 0, v7, vcc
	global_load_dword v19, v[8:9], off
	v_add_co_u32_e32 v8, vcc, s0, v6
	s_mov_b32 s0, 0x3a000
	s_nop 0
	v_addc_co_u32_e32 v9, vcc, 0, v7, vcc
	global_load_dword v20, v[8:9], off
	v_add_co_u32_e32 v8, vcc, s0, v6
	s_mov_b32 s0, 0x3b000
	s_nop 0
	v_addc_co_u32_e32 v9, vcc, 0, v7, vcc
	global_load_dword v21, v[8:9], off
	v_add_co_u32_e32 v8, vcc, s0, v6
	s_mov_b32 s0, 0x3c000
	s_nop 0
	v_addc_co_u32_e32 v9, vcc, 0, v7, vcc
	global_load_dword v22, v[8:9], off
	v_add_co_u32_e32 v8, vcc, s0, v6
	s_mov_b32 s0, 0x3d000
	s_nop 0
	v_addc_co_u32_e32 v9, vcc, 0, v7, vcc
	global_load_dword v23, v[8:9], off
	v_add_co_u32_e32 v8, vcc, s0, v6
	s_mov_b32 s0, 0x3e000
	s_nop 0
	v_addc_co_u32_e32 v9, vcc, 0, v7, vcc
	global_load_dword v24, v[8:9], off
	v_add_co_u32_e32 v8, vcc, s0, v6
	s_mov_b32 s0, 0x3f000
	s_nop 0
	v_addc_co_u32_e32 v9, vcc, 0, v7, vcc
	global_load_dword v8, v[8:9], off
	v_add_co_u32_e32 v6, vcc, s0, v6
	s_nop 1
	v_addc_co_u32_e32 v7, vcc, 0, v7, vcc
	global_load_dword v6, v[6:7], off
	s_waitcnt vmcnt(0) lgkmcnt(0)
; __device__ __forceinline__ float f16_lo(unsigned w) { return (float)__builtin_bit_cast(_Float16, (unsigned short)(w & 0xffffu)); }
; __device__ __forceinline__ float f16_hi(unsigned w) { return (float)__builtin_bit_cast(_Float16, (unsigned short)(w >> 16)); }
;     __device__ __forceinline__ void operator()(const f32x4 (&acc)[2][2][4][2], const Unit& u, int wr, int wc, int fr, int fq) const {
;     ...
;         { const int t = (4 * wr + wc) * 64 + fq * 16 + fr, chunk = t >> 7, c = (u.pn >> 1) * 256 + (u.pn & 1) * 128 + (t & 127), r0 = u.pm * BM + chunk * 64;
;           const unsigned* ab = AB + (size_t)r0 * D + c; float h = 0.f, L = 0.f;
; #pragma unroll
;           for (int b4 = 0; b4 < 4; ++b4) { unsigned w[16];
; #pragma unroll
;               for (int i = 0; i < 16; ++i) w[i] = ab[(size_t)(b4 * 16 + i) * D];
; #pragma unroll
;               for (int i = 0; i < 16; ++i) { const float la = f16_lo(w[i]); h = __expf(la) * h + f16_hi(w[i]); L += la; } }
;           const size_t o = (size_t)(r0 >> 6) * 1024 + c; Ls[o] = L; Hs[o] = h; }
	v_cvt_f32_f16_e32 v7, v11
	s_and_b64 vcc, exec, s[4:5]
	v_mul_f32_e32 v9, 0x3fb8aa3b, v7
	v_exp_f32_e32 v9, v9
	v_add_f32_e32 v7, v10, v7
	v_fma_mix_f32 v5, v9, v5, v11 op_sel:[0,0,1] op_sel_hi:[0,0,1]
	v_cvt_f32_f16_e32 v9, v12
	v_mul_f32_e32 v10, 0x3fb8aa3b, v9
	v_exp_f32_e32 v10, v10
	v_add_f32_e32 v7, v7, v9
	v_cvt_f32_f16_e32 v9, v13
	v_fma_mix_f32 v5, v10, v5, v12 op_sel:[0,0,1] op_sel_hi:[0,0,1]
	v_mul_f32_e32 v10, 0x3fb8aa3b, v9
	v_exp_f32_e32 v10, v10
	v_add_f32_e32 v7, v7, v9
	v_cvt_f32_f16_e32 v9, v14
	v_fma_mix_f32 v5, v10, v5, v13 op_sel:[0,0,1] op_sel_hi:[0,0,1]
	v_mul_f32_e32 v10, 0x3fb8aa3b, v9
	v_exp_f32_e32 v10, v10
	v_add_f32_e32 v7, v7, v9
	v_cvt_f32_f16_e32 v9, v15
	v_fma_mix_f32 v5, v10, v5, v14 op_sel:[0,0,1] op_sel_hi:[0,0,1]
	v_mul_f32_e32 v10, 0x3fb8aa3b, v9
	v_exp_f32_e32 v10, v10
	v_add_f32_e32 v7, v7, v9
	v_cvt_f32_f16_e32 v9, v16
	v_fma_mix_f32 v5, v10, v5, v15 op_sel:[0,0,1] op_sel_hi:[0,0,1]
	v_mul_f32_e32 v10, 0x3fb8aa3b, v9
	v_exp_f32_e32 v10, v10
	v_add_f32_e32 v7, v7, v9
	v_cvt_f32_f16_e32 v9, v17
	v_fma_mix_f32 v5, v10, v5, v16 op_sel:[0,0,1] op_sel_hi:[0,0,1]
	v_mul_f32_e32 v10, 0x3fb8aa3b, v9
	v_exp_f32_e32 v10, v10
	v_add_f32_e32 v7, v7, v9
	v_cvt_f32_f16_e32 v9, v18
	v_fma_mix_f32 v5, v10, v5, v17 op_sel:[0,0,1] op_sel_hi:[0,0,1]
	v_mul_f32_e32 v10, 0x3fb8aa3b, v9
	v_exp_f32_e32 v10, v10
	v_add_f32_e32 v7, v7, v9
	v_cvt_f32_f16_e32 v9, v19
	v_fma_mix_f32 v5, v10, v5, v18 op_sel:[0,0,1] op_sel_hi:[0,0,1]
	v_mul_f32_e32 v10, 0x3fb8aa3b, v9
	v_exp_f32_e32 v10, v10
	v_add_f32_e32 v7, v7, v9
	v_cvt_f32_f16_e32 v9, v20
	v_fma_mix_f32 v5, v10, v5, v19 op_sel:[0,0,1] op_sel_hi:[0,0,1]
	v_mul_f32_e32 v10, 0x3fb8aa3b, v9
	v_exp_f32_e32 v10, v10
	v_add_f32_e32 v7, v7, v9
	v_cvt_f32_f16_e32 v9, v21
	v_fma_mix_f32 v5, v10, v5, v20 op_sel:[0,0,1] op_sel_hi:[0,0,1]
	v_mul_f32_e32 v10, 0x3fb8aa3b, v9
	v_exp_f32_e32 v10, v10
	v_add_f32_e32 v7, v7, v9
	v_cvt_f32_f16_e32 v9, v22
	v_fma_mix_f32 v5, v10, v5, v21 op_sel:[0,0,1] op_sel_hi:[0,0,1]
	v_mul_f32_e32 v10, 0x3fb8aa3b, v9
	v_exp_f32_e32 v10, v10
	v_add_f32_e32 v7, v7, v9
	v_cvt_f32_f16_e32 v9, v23
	v_fma_mix_f32 v5, v10, v5, v22 op_sel:[0,0,1] op_sel_hi:[0,0,1]
	v_mul_f32_e32 v10, 0x3fb8aa3b, v9
	v_exp_f32_e32 v10, v10
	v_add_f32_e32 v7, v7, v9
	v_cvt_f32_f16_e32 v9, v24
	v_fma_mix_f32 v5, v10, v5, v23 op_sel:[0,0,1] op_sel_hi:[0,0,1]
	v_mul_f32_e32 v10, 0x3fb8aa3b, v9
	v_exp_f32_e32 v10, v10
	v_add_f32_e32 v7, v7, v9
	v_cvt_f32_f16_e32 v9, v8
	v_fma_mix_f32 v5, v10, v5, v24 op_sel:[0,0,1] op_sel_hi:[0,0,1]
	v_mul_f32_e32 v10, 0x3fb8aa3b, v9
	v_exp_f32_e32 v10, v10
	v_add_f32_e32 v7, v7, v9
	v_fma_mix_f32 v5, v10, v5, v8 op_sel:[0,0,1] op_sel_hi:[0,0,1]
	v_cvt_f32_f16_e32 v8, v6
	v_mul_f32_e32 v9, 0x3fb8aa3b, v8
	v_exp_f32_e32 v9, v9
	v_add_f32_e32 v7, v7, v8
	v_fma_mix_f32 v6, v9, v5, v6 op_sel:[0,0,1] op_sel_hi:[0,0,1]
	v_ashrrev_i32_e32 v5, 31, v4
	v_lshlrev_b64 v[4:5], 10, v[4:5]
	v_lshl_add_u64 v[2:3], v[4:5], 0, v[2:3]
	v_lshlrev_b64 v[2:3], 2, v[2:3]
	v_lshl_add_u64 v[4:5], s[74:75], 0, v[2:3]
	v_lshl_add_u64 v[2:3], s[22:23], 0, v[2:3]
	global_store_dword v[4:5], v7, off
	global_store_dword v[2:3], v6, off
	s_cbranch_vccnz .LBB0_172
	s_andn2_b64 vcc, exec, s[18:19]
	s_cbranch_vccnz .LBB0_171
	s_barrier
	s_branch .LBB0_171

; template <class Epi>
; __device__ __forceinline__ void gemm_phase(LAS unsigned char* lds, const Gemm g, const StaticOrder& S, const Epi& E, const int tid) {
;     ...
; #pragma unroll
;         for (int a = 0; a < 2; ++a)
; #pragma unroll
;             for (int b = 0; b < 2; ++b)
; #pragma unroll
;                 for (int m = 0; m < 4; ++m)
; #pragma unroll
;                     for (int n = 0; n < 2; ++n) acc[a][b][m][n] = (f32x4){0.f, 0.f, 0.f, 0.f};
.LBB0_296:
	v_mov_b32_e32 v125, 0
	s_andn2_b64 vcc, exec, s[24:25]
	s_cbranch_vccnz .LBB0_300
	s_add_u32 s0, s34, 0x100
	s_addc_u32 s1, s35, 0
	s_add_u32 s6, s36, 0x80
	v_mov_b32_e32 v2, 0
	s_addc_u32 s7, s37, 0
	s_mov_b32 s34, 0
	v_mov_b32_e32 v3, v2
	v_mov_b32_e32 v4, v2
	v_mov_b32_e32 v5, v2
	v_mov_b32_e32 v6, v2
	v_mov_b32_e32 v7, v2
	v_mov_b32_e32 v8, v2
	v_mov_b32_e32 v9, v2
	v_mov_b32_e32 v18, v2
	v_mov_b32_e32 v19, v2
	v_mov_b32_e32 v20, v2
	v_mov_b32_e32 v21, v2
	v_mov_b32_e32 v22, v2
	v_mov_b32_e32 v23, v2
	v_mov_b32_e32 v24, v2
	v_mov_b32_e32 v25, v2
	v_mov_b32_e32 v34, v2
	v_mov_b32_e32 v35, v2
	v_mov_b32_e32 v36, v2
	v_mov_b32_e32 v37, v2
	v_mov_b32_e32 v38, v2
	v_mov_b32_e32 v39, v2
	v_mov_b32_e32 v40, v2
	v_mov_b32_e32 v41, v2
	v_mov_b32_e32 v50, v2
	v_mov_b32_e32 v51, v2
	v_mov_b32_e32 v52, v2
	v_mov_b32_e32 v53, v2
	v_mov_b32_e32 v54, v2
	v_mov_b32_e32 v55, v2
	v_mov_b32_e32 v56, v2
	v_mov_b32_e32 v57, v2
	v_mov_b32_e32 v10, v2
	v_mov_b32_e32 v11, v2
	v_mov_b32_e32 v12, v2
	v_mov_b32_e32 v13, v2
	v_mov_b32_e32 v14, v2
	v_mov_b32_e32 v15, v2
	v_mov_b32_e32 v16, v2
	v_mov_b32_e32 v17, v2
	v_mov_b32_e32 v26, v2
	v_mov_b32_e32 v27, v2
	v_mov_b32_e32 v28, v2
	v_mov_b32_e32 v29, v2
	v_mov_b32_e32 v30, v2
	v_mov_b32_e32 v31, v2
	v_mov_b32_e32 v32, v2
	v_mov_b32_e32 v33, v2
	v_mov_b32_e32 v42, v2
	v_mov_b32_e32 v43, v2
	v_mov_b32_e32 v44, v2
	v_mov_b32_e32 v45, v2
	v_mov_b32_e32 v46, v2
	v_mov_b32_e32 v47, v2
	v_mov_b32_e32 v48, v2
	v_mov_b32_e32 v49, v2
	v_mov_b32_e32 v58, v2
	v_mov_b32_e32 v59, v2
	v_mov_b32_e32 v60, v2
	v_mov_b32_e32 v61, v2
	v_mov_b32_e32 v62, v2
	v_mov_b32_e32 v63, v2
	v_mov_b32_e32 v64, v2
	v_mov_b32_e32 v65, v2
	v_mov_b32_e32 v66, v2
	v_mov_b32_e32 v67, v2
	v_mov_b32_e32 v68, v2
	v_mov_b32_e32 v69, v2
	v_mov_b32_e32 v70, v2
	v_mov_b32_e32 v71, v2
	v_mov_b32_e32 v72, v2
	v_mov_b32_e32 v73, v2
	v_mov_b32_e32 v82, v2
	v_mov_b32_e32 v83, v2
	v_mov_b32_e32 v84, v2
	v_mov_b32_e32 v85, v2
	v_mov_b32_e32 v86, v2
	v_mov_b32_e32 v87, v2
	v_mov_b32_e32 v88, v2
	v_mov_b32_e32 v89, v2
	v_mov_b32_e32 v98, v2
	v_mov_b32_e32 v99, v2
	v_mov_b32_e32 v100, v2
	v_mov_b32_e32 v101, v2
	v_mov_b32_e32 v102, v2
	v_mov_b32_e32 v103, v2
	v_mov_b32_e32 v104, v2
	v_mov_b32_e32 v105, v2
	v_mov_b32_e32 v114, v2
	v_mov_b32_e32 v115, v2
	v_mov_b32_e32 v116, v2
	v_mov_b32_e32 v117, v2
	v_mov_b32_e32 v118, v2
	v_mov_b32_e32 v119, v2
	v_mov_b32_e32 v120, v2
	v_mov_b32_e32 v121, v2
	v_mov_b32_e32 v74, v2
	v_mov_b32_e32 v75, v2
	v_mov_b32_e32 v76, v2
	v_mov_b32_e32 v77, v2
	v_mov_b32_e32 v78, v2
	v_mov_b32_e32 v79, v2
	v_mov_b32_e32 v80, v2
	v_mov_b32_e32 v81, v2
	v_mov_b32_e32 v90, v2
	v_mov_b32_e32 v91, v2
	v_mov_b32_e32 v92, v2
	v_mov_b32_e32 v93, v2
	v_mov_b32_e32 v94, v2
	v_mov_b32_e32 v95, v2
	v_mov_b32_e32 v96, v2
	v_mov_b32_e32 v97, v2
	v_mov_b32_e32 v106, v2
	v_mov_b32_e32 v107, v2
	v_mov_b32_e32 v108, v2
	v_mov_b32_e32 v109, v2
	v_mov_b32_e32 v110, v2
	v_mov_b32_e32 v111, v2
	v_mov_b32_e32 v112, v2
	v_mov_b32_e32 v113, v2
	v_mov_b32_e32 v126, v2
	v_mov_b32_e32 v127, v2
	v_mov_b32_e32 v128, v2
	v_mov_b32_e32 v129, v2
	v_mov_b32_e32 v122, v2
	v_mov_b32_e32 v123, v2
	v_mov_b32_e32 v124, v2
	v_mov_b32_e32 v125, v2

; template <class Epi>
; __device__ __forceinline__ void gemm_phase(LAS unsigned char* lds, const Gemm g, const StaticOrder& S, const Epi& E, const int tid) {
;     ...
; #pragma unroll
;         for (int a = 0; a < 2; ++a)
; #pragma unroll
;             for (int b = 0; b < 2; ++b)
; #pragma unroll
;                 for (int m = 0; m < 4; ++m)
; #pragma unroll
;                     for (int n = 0; n < 2; ++n) acc[a][b][m][n] = (f32x4){0.f, 0.f, 0.f, 0.f};
.LBB0_346:
	v_mov_b32_e32 v125, 0
	s_andn2_b64 vcc, exec, s[10:11]
	s_cbranch_vccnz .LBB0_349
	s_add_u32 s0, s36, 0x100
	s_addc_u32 s1, s37, 0
	s_add_u32 s36, s38, 0x80
	v_mov_b32_e32 v2, 0
	s_addc_u32 s37, s39, 0
	s_mov_b32 s38, 0
	v_mov_b32_e32 v3, v2
	v_mov_b32_e32 v4, v2
	v_mov_b32_e32 v5, v2
	v_mov_b32_e32 v6, v2
	v_mov_b32_e32 v7, v2
	v_mov_b32_e32 v8, v2
	v_mov_b32_e32 v9, v2
	v_mov_b32_e32 v18, v2
	v_mov_b32_e32 v19, v2
	v_mov_b32_e32 v20, v2
	v_mov_b32_e32 v21, v2
	v_mov_b32_e32 v22, v2
	v_mov_b32_e32 v23, v2
	v_mov_b32_e32 v24, v2
	v_mov_b32_e32 v25, v2
	v_mov_b32_e32 v34, v2
	v_mov_b32_e32 v35, v2
	v_mov_b32_e32 v36, v2
	v_mov_b32_e32 v37, v2
	v_mov_b32_e32 v38, v2
	v_mov_b32_e32 v39, v2
	v_mov_b32_e32 v40, v2
	v_mov_b32_e32 v41, v2
	v_mov_b32_e32 v50, v2
	v_mov_b32_e32 v51, v2
	v_mov_b32_e32 v52, v2
	v_mov_b32_e32 v53, v2
	v_mov_b32_e32 v54, v2
	v_mov_b32_e32 v55, v2
	v_mov_b32_e32 v56, v2
	v_mov_b32_e32 v57, v2
	v_mov_b32_e32 v10, v2
	v_mov_b32_e32 v11, v2
	v_mov_b32_e32 v12, v2
	v_mov_b32_e32 v13, v2
	v_mov_b32_e32 v14, v2
	v_mov_b32_e32 v15, v2
	v_mov_b32_e32 v16, v2
	v_mov_b32_e32 v17, v2
	v_mov_b32_e32 v26, v2
	v_mov_b32_e32 v27, v2
	v_mov_b32_e32 v28, v2
	v_mov_b32_e32 v29, v2
	v_mov_b32_e32 v30, v2
	v_mov_b32_e32 v31, v2
	v_mov_b32_e32 v32, v2
	v_mov_b32_e32 v33, v2
	v_mov_b32_e32 v42, v2
	v_mov_b32_e32 v43, v2
	v_mov_b32_e32 v44, v2
	v_mov_b32_e32 v45, v2
	v_mov_b32_e32 v46, v2
	v_mov_b32_e32 v47, v2
	v_mov_b32_e32 v48, v2
	v_mov_b32_e32 v49, v2
	v_mov_b32_e32 v58, v2
	v_mov_b32_e32 v59, v2
	v_mov_b32_e32 v60, v2
	v_mov_b32_e32 v61, v2
	v_mov_b32_e32 v62, v2
	v_mov_b32_e32 v63, v2
	v_mov_b32_e32 v64, v2
	v_mov_b32_e32 v65, v2
	v_mov_b32_e32 v66, v2
	v_mov_b32_e32 v67, v2
	v_mov_b32_e32 v68, v2
	v_mov_b32_e32 v69, v2
	v_mov_b32_e32 v70, v2
	v_mov_b32_e32 v71, v2
	v_mov_b32_e32 v72, v2
	v_mov_b32_e32 v73, v2
	v_mov_b32_e32 v82, v2
	v_mov_b32_e32 v83, v2
	v_mov_b32_e32 v84, v2
	v_mov_b32_e32 v85, v2
	v_mov_b32_e32 v86, v2
	v_mov_b32_e32 v87, v2
	v_mov_b32_e32 v88, v2
	v_mov_b32_e32 v89, v2
	v_mov_b32_e32 v98, v2
	v_mov_b32_e32 v99, v2
	v_mov_b32_e32 v100, v2
	v_mov_b32_e32 v101, v2
	v_mov_b32_e32 v102, v2
	v_mov_b32_e32 v103, v2
	v_mov_b32_e32 v104, v2
	v_mov_b32_e32 v105, v2
	v_mov_b32_e32 v114, v2
	v_mov_b32_e32 v115, v2
	v_mov_b32_e32 v116, v2
	v_mov_b32_e32 v117, v2
	v_mov_b32_e32 v118, v2
	v_mov_b32_e32 v119, v2
	v_mov_b32_e32 v120, v2
	v_mov_b32_e32 v121, v2
	v_mov_b32_e32 v74, v2
	v_mov_b32_e32 v75, v2
	v_mov_b32_e32 v76, v2
	v_mov_b32_e32 v77, v2
	v_mov_b32_e32 v78, v2
	v_mov_b32_e32 v79, v2
	v_mov_b32_e32 v80, v2
	v_mov_b32_e32 v81, v2
	v_mov_b32_e32 v90, v2
	v_mov_b32_e32 v91, v2
	v_mov_b32_e32 v92, v2
	v_mov_b32_e32 v93, v2
	v_mov_b32_e32 v94, v2
	v_mov_b32_e32 v95, v2
	v_mov_b32_e32 v96, v2
	v_mov_b32_e32 v97, v2
	v_mov_b32_e32 v106, v2
	v_mov_b32_e32 v107, v2
	v_mov_b32_e32 v108, v2
	v_mov_b32_e32 v109, v2
	v_mov_b32_e32 v110, v2
	v_mov_b32_e32 v111, v2
	v_mov_b32_e32 v112, v2
	v_mov_b32_e32 v113, v2
	v_mov_b32_e32 v126, v2
	v_mov_b32_e32 v127, v2
	v_mov_b32_e32 v128, v2
	v_mov_b32_e32 v129, v2
	v_mov_b32_e32 v122, v2
	v_mov_b32_e32 v123, v2
	v_mov_b32_e32 v124, v2
	v_mov_b32_e32 v125, v2

; template <class Epi>
; __device__ __forceinline__ void gemm_phase(LAS unsigned char* lds, const Gemm g, const StaticOrder& S, const Epi& E, const int tid) {
;     ...
; #pragma unroll
;         for (int a = 0; a < 2; ++a)
; #pragma unroll
;             for (int b = 0; b < 2; ++b)
; #pragma unroll
;                 for (int m = 0; m < 4; ++m)
; #pragma unroll
;                     for (int n = 0; n < 2; ++n) acc[a][b][m][n] = (f32x4){0.f, 0.f, 0.f, 0.f};
.LBB0_425:
	v_mov_b32_e32 v145, 0
	s_andn2_b64 vcc, exec, s[48:49]
	s_cbranch_vccnz .LBB0_428
	s_add_u32 s0, s66, 0x100
	s_addc_u32 s1, s67, 0
	s_add_u32 s6, s68, 0x80
	v_mov_b32_e32 v2, 0
	s_addc_u32 s7, s69, 0
	s_mov_b32 s8, 0
	v_mov_b32_e32 v3, v2
	v_mov_b32_e32 v4, v2
	v_mov_b32_e32 v5, v2
	v_mov_b32_e32 v6, v2
	v_mov_b32_e32 v7, v2
	v_mov_b32_e32 v8, v2
	v_mov_b32_e32 v9, v2
	v_mov_b32_e32 v18, v2
	v_mov_b32_e32 v19, v2
	v_mov_b32_e32 v20, v2
	v_mov_b32_e32 v21, v2
	v_mov_b32_e32 v22, v2
	v_mov_b32_e32 v23, v2
	v_mov_b32_e32 v24, v2
	v_mov_b32_e32 v25, v2
	v_mov_b32_e32 v34, v2
	v_mov_b32_e32 v35, v2
	v_mov_b32_e32 v36, v2
	v_mov_b32_e32 v37, v2
	v_mov_b32_e32 v38, v2
	v_mov_b32_e32 v39, v2
	v_mov_b32_e32 v40, v2
	v_mov_b32_e32 v41, v2
	v_mov_b32_e32 v50, v2
	v_mov_b32_e32 v51, v2
	v_mov_b32_e32 v52, v2
	v_mov_b32_e32 v53, v2
	v_mov_b32_e32 v54, v2
	v_mov_b32_e32 v55, v2
	v_mov_b32_e32 v56, v2
	v_mov_b32_e32 v57, v2
	v_mov_b32_e32 v10, v2
	v_mov_b32_e32 v11, v2
	v_mov_b32_e32 v12, v2
	v_mov_b32_e32 v13, v2
	v_mov_b32_e32 v14, v2
	v_mov_b32_e32 v15, v2
	v_mov_b32_e32 v16, v2
	v_mov_b32_e32 v17, v2
	v_mov_b32_e32 v26, v2
	v_mov_b32_e32 v27, v2
	v_mov_b32_e32 v28, v2
	v_mov_b32_e32 v29, v2
	v_mov_b32_e32 v30, v2
	v_mov_b32_e32 v31, v2
	v_mov_b32_e32 v32, v2
	v_mov_b32_e32 v33, v2
	v_mov_b32_e32 v42, v2
	v_mov_b32_e32 v43, v2
	v_mov_b32_e32 v44, v2
	v_mov_b32_e32 v45, v2
	v_mov_b32_e32 v46, v2
	v_mov_b32_e32 v47, v2
	v_mov_b32_e32 v48, v2
	v_mov_b32_e32 v49, v2
	v_mov_b32_e32 v58, v2
	v_mov_b32_e32 v59, v2
	v_mov_b32_e32 v60, v2
	v_mov_b32_e32 v61, v2
	v_mov_b32_e32 v62, v2
	v_mov_b32_e32 v63, v2
	v_mov_b32_e32 v64, v2
	v_mov_b32_e32 v65, v2
	v_mov_b32_e32 v82, v2
	v_mov_b32_e32 v83, v2
	v_mov_b32_e32 v84, v2
	v_mov_b32_e32 v85, v2
	v_mov_b32_e32 v86, v2
	v_mov_b32_e32 v87, v2
	v_mov_b32_e32 v88, v2
	v_mov_b32_e32 v89, v2
	v_mov_b32_e32 v98, v2
	v_mov_b32_e32 v99, v2
	v_mov_b32_e32 v100, v2
	v_mov_b32_e32 v101, v2
	v_mov_b32_e32 v102, v2
	v_mov_b32_e32 v103, v2
	v_mov_b32_e32 v104, v2
	v_mov_b32_e32 v105, v2
	v_mov_b32_e32 v114, v2
	v_mov_b32_e32 v115, v2
	v_mov_b32_e32 v116, v2
	v_mov_b32_e32 v117, v2
	v_mov_b32_e32 v118, v2
	v_mov_b32_e32 v119, v2
	v_mov_b32_e32 v120, v2
	v_mov_b32_e32 v121, v2
	v_mov_b32_e32 v130, v2
	v_mov_b32_e32 v131, v2
	v_mov_b32_e32 v132, v2
	v_mov_b32_e32 v133, v2
	v_mov_b32_e32 v134, v2
	v_mov_b32_e32 v135, v2
	v_mov_b32_e32 v136, v2
	v_mov_b32_e32 v137, v2
	v_mov_b32_e32 v90, v2
	v_mov_b32_e32 v91, v2
	v_mov_b32_e32 v92, v2
	v_mov_b32_e32 v93, v2
	v_mov_b32_e32 v94, v2
	v_mov_b32_e32 v95, v2
	v_mov_b32_e32 v96, v2
	v_mov_b32_e32 v97, v2
	v_mov_b32_e32 v106, v2
	v_mov_b32_e32 v107, v2
	v_mov_b32_e32 v108, v2
	v_mov_b32_e32 v109, v2
	v_mov_b32_e32 v110, v2
	v_mov_b32_e32 v111, v2
	v_mov_b32_e32 v112, v2
	v_mov_b32_e32 v113, v2
	v_mov_b32_e32 v122, v2
	v_mov_b32_e32 v123, v2
	v_mov_b32_e32 v124, v2
	v_mov_b32_e32 v125, v2
	v_mov_b32_e32 v126, v2
	v_mov_b32_e32 v127, v2
	v_mov_b32_e32 v128, v2
	v_mov_b32_e32 v129, v2
	v_mov_b32_e32 v138, v2
	v_mov_b32_e32 v139, v2
	v_mov_b32_e32 v140, v2
	v_mov_b32_e32 v141, v2
	v_mov_b32_e32 v142, v2
	v_mov_b32_e32 v143, v2
	v_mov_b32_e32 v144, v2
	v_mov_b32_e32 v145, v2

; template <class Epi>
; __device__ __forceinline__ void gemm_phase(LAS unsigned char* lds, const Gemm g, const StaticOrder& S, const Epi& E, const int tid) {
;     ...
; #pragma unroll
;         for (int a = 0; a < 2; ++a)
; #pragma unroll
;             for (int b = 0; b < 2; ++b)
; #pragma unroll
;                 for (int m = 0; m < 4; ++m)
; #pragma unroll
;                     for (int n = 0; n < 2; ++n) acc[a][b][m][n] = (f32x4){0.f, 0.f, 0.f, 0.f};
.LBB0_650:
	v_mov_b32_e32 v113, 0
	s_andn2_b64 vcc, exec, s[24:25]
	s_cbranch_vccnz .LBB0_653
	s_add_u32 s21, s8, 0x100
	s_addc_u32 s42, s9, 0
	s_add_u32 s6, s10, 0x80
	v_mov_b32_e32 v14, 0
	s_addc_u32 s7, s11, 0
	s_mov_b32 s8, 0
	v_mov_b32_e32 v15, v14
	v_mov_b32_e32 v16, v14
	v_mov_b32_e32 v17, v14
	v_mov_b32_e32 v78, v14
	v_mov_b32_e32 v79, v14
	v_mov_b32_e32 v80, v14
	v_mov_b32_e32 v81, v14
	v_mov_b32_e32 v6, v14
	v_mov_b32_e32 v7, v14
	v_mov_b32_e32 v8, v14
	v_mov_b32_e32 v9, v14
	v_mov_b32_e32 v54, v14
	v_mov_b32_e32 v55, v14
	v_mov_b32_e32 v56, v14
	v_mov_b32_e32 v57, v14
	v_mov_b32_e32 v22, v14
	v_mov_b32_e32 v23, v14
	v_mov_b32_e32 v24, v14
	v_mov_b32_e32 v25, v14
	v_mov_b32_e32 v26, v14
	v_mov_b32_e32 v27, v14
	v_mov_b32_e32 v28, v14
	v_mov_b32_e32 v29, v14
	v_mov_b32_e32 v34, v14
	v_mov_b32_e32 v35, v14
	v_mov_b32_e32 v36, v14
	v_mov_b32_e32 v37, v14
	v_mov_b32_e32 v42, v14
	v_mov_b32_e32 v43, v14
	v_mov_b32_e32 v44, v14
	v_mov_b32_e32 v45, v14
	v_mov_b32_e32 v10, v14
	v_mov_b32_e32 v11, v14
	v_mov_b32_e32 v12, v14
	v_mov_b32_e32 v13, v14
	v_mov_b32_e32 v74, v14
	v_mov_b32_e32 v75, v14
	v_mov_b32_e32 v76, v14
	v_mov_b32_e32 v77, v14
	v_mov_b32_e32 v2, v14
	v_mov_b32_e32 v3, v14
	v_mov_b32_e32 v4, v14
	v_mov_b32_e32 v5, v14
	v_mov_b32_e32 v50, v14
	v_mov_b32_e32 v51, v14
	v_mov_b32_e32 v52, v14
	v_mov_b32_e32 v53, v14
	v_mov_b32_e32 v18, v14
	v_mov_b32_e32 v19, v14
	v_mov_b32_e32 v20, v14
	v_mov_b32_e32 v21, v14
	v_mov_b32_e32 v38, v14
	v_mov_b32_e32 v39, v14
	v_mov_b32_e32 v40, v14
	v_mov_b32_e32 v41, v14
	v_mov_b32_e32 v30, v14
	v_mov_b32_e32 v31, v14
	v_mov_b32_e32 v32, v14
	v_mov_b32_e32 v33, v14
	v_mov_b32_e32 v46, v14
	v_mov_b32_e32 v47, v14
	v_mov_b32_e32 v48, v14
	v_mov_b32_e32 v49, v14
	v_mov_b32_e32 v66, v14
	v_mov_b32_e32 v67, v14
	v_mov_b32_e32 v68, v14
	v_mov_b32_e32 v69, v14
	v_mov_b32_e32 v122, v14
	v_mov_b32_e32 v123, v14
	v_mov_b32_e32 v124, v14
	v_mov_b32_e32 v125, v14
	v_mov_b32_e32 v58, v14
	v_mov_b32_e32 v59, v14
	v_mov_b32_e32 v60, v14
	v_mov_b32_e32 v61, v14
	v_mov_b32_e32 v118, v14
	v_mov_b32_e32 v119, v14
	v_mov_b32_e32 v120, v14
	v_mov_b32_e32 v121, v14
	v_mov_b32_e32 v82, v14
	v_mov_b32_e32 v83, v14
	v_mov_b32_e32 v84, v14
	v_mov_b32_e32 v85, v14
	v_mov_b32_e32 v86, v14
	v_mov_b32_e32 v87, v14
	v_mov_b32_e32 v88, v14
	v_mov_b32_e32 v89, v14
	v_mov_b32_e32 v98, v14
	v_mov_b32_e32 v99, v14
	v_mov_b32_e32 v100, v14
	v_mov_b32_e32 v101, v14
	v_mov_b32_e32 v102, v14
	v_mov_b32_e32 v103, v14
	v_mov_b32_e32 v104, v14
	v_mov_b32_e32 v105, v14
	v_mov_b32_e32 v70, v14
	v_mov_b32_e32 v71, v14
	v_mov_b32_e32 v72, v14
	v_mov_b32_e32 v73, v14
	v_mov_b32_e32 v126, v14
	v_mov_b32_e32 v127, v14
	v_mov_b32_e32 v128, v14
	v_mov_b32_e32 v129, v14
	v_mov_b32_e32 v62, v14
	v_mov_b32_e32 v63, v14
	v_mov_b32_e32 v64, v14
	v_mov_b32_e32 v65, v14
	v_mov_b32_e32 v114, v14
	v_mov_b32_e32 v115, v14
	v_mov_b32_e32 v116, v14
	v_mov_b32_e32 v117, v14
	v_mov_b32_e32 v90, v14
	v_mov_b32_e32 v91, v14
	v_mov_b32_e32 v92, v14
	v_mov_b32_e32 v93, v14
	v_mov_b32_e32 v94, v14
	v_mov_b32_e32 v95, v14
	v_mov_b32_e32 v96, v14
	v_mov_b32_e32 v97, v14
	v_mov_b32_e32 v106, v14
	v_mov_b32_e32 v107, v14
	v_mov_b32_e32 v108, v14
	v_mov_b32_e32 v109, v14
	v_mov_b32_e32 v110, v14
	v_mov_b32_e32 v111, v14
	v_mov_b32_e32 v112, v14
	v_mov_b32_e32 v113, v14

; __device__ __forceinline__ unsigned xb_ld(unsigned* p)              { return __hip_atomic_load(p, __ATOMIC_RELAXED, __HIP_MEMORY_SCOPE_AGENT); }
; __device__ __forceinline__ void xcd_barrier_complete(unsigned* bar, unsigned x, unsigned& nloc, unsigned& nx) {
;     ...
;     for (;;) {
;         sum = 0u; cnt = 0u; mine = 0u;
; #pragma unroll
;         for (unsigned j = 0; j < 16; ++j) { const unsigned c = xb_ld(&bar[XB_XCNT(j)]); sum += c; cnt += (c > 0u) ? 1u : 0u; mine = (j == x) ? c : mine; }
;         if (sum == G) break;
;         __builtin_amdgcn_s_sleep(1);
;         if ((++sp & 255u) == 0u) { if (xb_ld(&bar[XB_TMO])) break; if (sp > XB_SPIN_CAP) { atomicAdd(&bar[XB_TMO], 1u); break; } }
;     }
.LBB0_1047:
	s_waitcnt lgkmcnt(0)
	global_load_dword v4, v1, s[50:51] sc1
	global_load_dword v0, v1, s[50:51] offset:256 sc1
	global_load_dword v2, v1, s[50:51] offset:512 sc1
	global_load_dword v3, v1, s[50:51] offset:768 sc1
	global_load_dword v5, v1, s[50:51] offset:1024 sc1
	global_load_dword v6, v1, s[50:51] offset:1280 sc1
	global_load_dword v7, v1, s[50:51] offset:1536 sc1
	global_load_dword v8, v1, s[50:51] offset:1792 sc1
	global_load_dword v9, v1, s[50:51] offset:2048 sc1
	global_load_dword v10, v1, s[50:51] offset:2304 sc1
	global_load_dword v11, v1, s[50:51] offset:2560 sc1
	global_load_dword v12, v1, s[50:51] offset:2816 sc1
	global_load_dword v13, v1, s[50:51] offset:3072 sc1
	global_load_dword v14, v1, s[50:51] offset:3328 sc1
	global_load_dword v15, v1, s[50:51] offset:3584 sc1
	global_load_dword v16, v1, s[50:51] offset:3840 sc1
	s_mov_b64 s[8:9], -1
	s_mov_b64 s[6:7], -1
	s_waitcnt vmcnt(0)
	v_add_u32_e32 v17, v0, v4
	v_add_u32_e32 v17, v17, v2
	v_add_u32_e32 v17, v17, v3
	v_add_u32_e32 v17, v17, v5
	v_add_u32_e32 v17, v17, v6
	v_add_u32_e32 v17, v17, v7
	v_add_u32_e32 v17, v17, v8
	v_add_u32_e32 v17, v17, v9
	v_add_u32_e32 v17, v17, v10
	v_add_u32_e32 v17, v17, v11
	v_add_u32_e32 v17, v17, v12
	v_add_u32_e32 v17, v17, v13
	v_add_u32_e32 v17, v17, v14
	v_add_u32_e32 v17, v17, v15
	v_add_u32_e32 v17, v17, v16
	v_cmp_eq_u32_e32 vcc, s49, v17
	s_cbranch_vccnz .LBB0_1046
	s_and_b32 s6, s12, 0xff
	s_cmp_eq_u32 s6, 0
	s_mov_b64 s[6:7], -1
	s_mov_b64 s[10:11], -1
	s_sleep 1
	s_cbranch_scc1 .LBB0_1051
	s_and_b64 vcc, exec, s[10:11]
	s_cbranch_vccz .LBB0_1046
